# v73 + remaining K-loop DMA address adds folded into SALU-computed SGPR bases (58 of 80 DMAs now SGPR-base form)
# speedup vs baseline: 1.0113x; 1.0058x over previous
.LBB0_267:
	s_add_i32 m0, s7, 0xc000
	ds_read_b128 v[160:163], v151
	ds_read_b128 v[164:167], v151 offset:1024
	ds_read_b128 v[168:171], v151 offset:2048
	ds_read_b128 v[172:175], v151 offset:3072
	ds_read_b128 v[176:179], v151 offset:4096
	ds_read_b128 v[180:183], v151 offset:5120
	ds_read_b128 v[184:187], v151 offset:6144
	ds_read_b128 v[190:193], v151 offset:7168
	global_load_lds_dwordx4 v138, s[4:5]
	s_add_i32 m0, s7, 0xe000
	s_nop 0
	global_load_lds_dwordx4 v140, s[4:5]
	s_waitcnt lgkmcnt(8)
	s_barrier
	s_waitcnt lgkmcnt(0)
	v_mfma_f32_16x16x32_bf16 v[126:129], v[142:145], v[160:163], v[126:129]
	v_mfma_f32_16x16x32_bf16 v[122:125], v[152:155], v[160:163], v[122:125]
	v_mfma_f32_16x16x32_bf16 v[110:113], v[142:145], v[168:171], v[110:113]
	v_mfma_f32_16x16x32_bf16 v[106:109], v[152:155], v[168:171], v[106:109]
	v_mfma_f32_16x16x32_bf16 v[94:97], v[142:145], v[176:179], v[94:97]
	v_mfma_f32_16x16x32_bf16 v[90:93], v[152:155], v[176:179], v[90:93]
	v_mfma_f32_16x16x32_bf16 v[78:81], v[142:145], v[184:187], v[78:81]
	v_mfma_f32_16x16x32_bf16 v[74:77], v[152:155], v[184:187], v[74:77]
	v_mfma_f32_16x16x32_bf16 v[126:129], v[146:149], v[164:167], v[126:129]
	v_mfma_f32_16x16x32_bf16 v[122:125], v[156:159], v[164:167], v[122:125]
	v_mfma_f32_16x16x32_bf16 v[110:113], v[146:149], v[172:175], v[110:113]
	v_mfma_f32_16x16x32_bf16 v[106:109], v[156:159], v[172:175], v[106:109]
	v_mfma_f32_16x16x32_bf16 v[94:97], v[146:149], v[180:183], v[94:97]
	v_mfma_f32_16x16x32_bf16 v[90:93], v[156:159], v[180:183], v[90:93]
	v_mfma_f32_16x16x32_bf16 v[78:81], v[146:149], v[190:193], v[78:81]
	v_mfma_f32_16x16x32_bf16 v[74:77], v[156:159], v[190:193], v[74:77]
	s_barrier
	s_add_i32 s88, 0, 0x14000
	s_add_i32 s86, s86, s22
	v_add_u32_e32 v0, s88, v150
	s_mov_b32 m0, s86
	ds_read_b128 v[194:197], v0
	ds_read_b128 v[198:201], v0 offset:1024
	ds_read_b128 v[202:205], v0 offset:2048
	ds_read_b128 v[206:209], v0 offset:3072
	global_load_lds_dwordx4 v134, s[12:13]
	s_add_i32 m0, s86, 0x2000
	s_nop 0
	global_load_lds_dwordx4 v130, s[12:13]
	s_barrier
	s_waitcnt lgkmcnt(0)
	v_mfma_f32_16x16x32_bf16 v[118:121], v[194:197], v[160:163], v[118:121]
	v_mfma_f32_16x16x32_bf16 v[114:117], v[202:205], v[160:163], v[114:117]
	v_mfma_f32_16x16x32_bf16 v[102:105], v[194:197], v[168:171], v[102:105]
	v_mfma_f32_16x16x32_bf16 v[98:101], v[202:205], v[168:171], v[98:101]
	v_mfma_f32_16x16x32_bf16 v[86:89], v[194:197], v[176:179], v[86:89]
	v_mfma_f32_16x16x32_bf16 v[82:85], v[202:205], v[176:179], v[82:85]
	v_mfma_f32_16x16x32_bf16 v[70:73], v[194:197], v[184:187], v[70:73]
	v_mfma_f32_16x16x32_bf16 v[66:69], v[202:205], v[184:187], v[66:69]
	v_mfma_f32_16x16x32_bf16 v[118:121], v[198:201], v[164:167], v[118:121]
	v_mfma_f32_16x16x32_bf16 v[114:117], v[206:209], v[164:167], v[114:117]
	v_mfma_f32_16x16x32_bf16 v[102:105], v[198:201], v[172:175], v[102:105]
	v_mfma_f32_16x16x32_bf16 v[98:101], v[206:209], v[172:175], v[98:101]
	v_mfma_f32_16x16x32_bf16 v[86:89], v[198:201], v[180:183], v[86:89]
	v_mfma_f32_16x16x32_bf16 v[82:85], v[206:209], v[180:183], v[82:85]
	v_mfma_f32_16x16x32_bf16 v[70:73], v[198:201], v[190:193], v[70:73]
	v_mfma_f32_16x16x32_bf16 v[66:69], v[206:209], v[190:193], v[66:69]
	s_mov_b32 m0, s7
	v_lshl_add_u64 v[214:215], s[14:15], 0, v[136:137]
	s_barrier
	ds_read_b128 v[160:163], v151 offset:16384
	ds_read_b128 v[164:167], v151 offset:17408
	ds_read_b128 v[168:171], v151 offset:18432
	ds_read_b128 v[172:175], v151 offset:19456
	ds_read_b128 v[176:179], v151 offset:20480
	ds_read_b128 v[180:183], v151 offset:21504
	ds_read_b128 v[184:187], v151 offset:22528
	ds_read_b128 v[190:193], v151 offset:23552
	global_load_lds_dwordx4 v[214:215], off
	s_mov_b32 m0, s23
	v_lshl_add_u64 v[216:217], s[14:15], 0, v[132:133]
	global_load_lds_dwordx4 v[216:217], off
	s_waitcnt vmcnt(10)
	s_barrier
	s_waitcnt lgkmcnt(0)
	v_mfma_f32_16x16x32_bf16 v[62:65], v[142:145], v[160:163], v[62:65]
	v_mfma_f32_16x16x32_bf16 v[58:61], v[152:155], v[160:163], v[58:61]
	v_mfma_f32_16x16x32_bf16 v[46:49], v[142:145], v[168:171], v[46:49]
	v_mfma_f32_16x16x32_bf16 v[42:45], v[152:155], v[168:171], v[42:45]
	v_mfma_f32_16x16x32_bf16 v[30:33], v[142:145], v[176:179], v[30:33]
	v_mfma_f32_16x16x32_bf16 v[26:29], v[152:155], v[176:179], v[26:29]
	v_mfma_f32_16x16x32_bf16 v[14:17], v[142:145], v[184:187], v[14:17]
	v_mfma_f32_16x16x32_bf16 v[10:13], v[152:155], v[184:187], v[10:13]
	v_mfma_f32_16x16x32_bf16 v[62:65], v[146:149], v[164:167], v[62:65]
	v_mfma_f32_16x16x32_bf16 v[58:61], v[156:159], v[164:167], v[58:61]
	v_mfma_f32_16x16x32_bf16 v[46:49], v[146:149], v[172:175], v[46:49]
	v_mfma_f32_16x16x32_bf16 v[42:45], v[156:159], v[172:175], v[42:45]
	v_mfma_f32_16x16x32_bf16 v[30:33], v[146:149], v[180:183], v[30:33]
	v_mfma_f32_16x16x32_bf16 v[26:29], v[156:159], v[180:183], v[26:29]
	v_mfma_f32_16x16x32_bf16 v[14:17], v[146:149], v[190:193], v[14:17]
	v_mfma_f32_16x16x32_bf16 v[10:13], v[156:159], v[190:193], v[10:13]
	s_barrier
	s_add_u32 s86, s12, 0x40000
	s_addc_u32 s87, s13, 0
	s_add_i32 s88, s88, s22
	s_mov_b32 m0, s88
	s_nop 0
	global_load_lds_dwordx4 v134, s[86:87]
	s_add_i32 m0, s88, 0x2000
	s_nop 0
	global_load_lds_dwordx4 v130, s[86:87]
	s_add_i32 s86, 0, 0x18000
	v_add_u32_e32 v0, s86, v150
	ds_read_b128 v[142:145], v0
	ds_read_b128 v[146:149], v0 offset:1024
	ds_read_b128 v[152:155], v0 offset:2048
	ds_read_b128 v[156:159], v0 offset:3072
	s_waitcnt vmcnt(6)
	s_barrier
	v_mfma_f32_16x16x32_bf16 v[54:57], v[194:197], v[160:163], v[54:57]
	v_mfma_f32_16x16x32_bf16 v[50:53], v[202:205], v[160:163], v[50:53]
	v_mfma_f32_16x16x32_bf16 v[38:41], v[194:197], v[168:171], v[38:41]
	v_mfma_f32_16x16x32_bf16 v[34:37], v[202:205], v[168:171], v[34:37]
	v_mfma_f32_16x16x32_bf16 v[22:25], v[194:197], v[176:179], v[22:25]
	v_mfma_f32_16x16x32_bf16 v[18:21], v[202:205], v[176:179], v[18:21]
	v_mfma_f32_16x16x32_bf16 v[6:9], v[194:197], v[184:187], v[6:9]
	v_mfma_f32_16x16x32_bf16 v[2:5], v[202:205], v[184:187], v[2:5]
	v_mfma_f32_16x16x32_bf16 v[54:57], v[198:201], v[164:167], v[54:57]
	v_mfma_f32_16x16x32_bf16 v[50:53], v[206:209], v[164:167], v[50:53]
	v_mfma_f32_16x16x32_bf16 v[38:41], v[198:201], v[172:175], v[38:41]
	v_mfma_f32_16x16x32_bf16 v[34:37], v[206:209], v[172:175], v[34:37]
	v_mfma_f32_16x16x32_bf16 v[22:25], v[198:201], v[180:183], v[22:25]
	v_mfma_f32_16x16x32_bf16 v[18:21], v[206:209], v[180:183], v[18:21]
	v_mfma_f32_16x16x32_bf16 v[6:9], v[198:201], v[190:193], v[6:9]
	v_mfma_f32_16x16x32_bf16 v[2:5], v[206:209], v[190:193], v[2:5]
	s_barrier
	s_add_u32 s14, s14, 0x40000
	s_addc_u32 s15, s15, 0
	s_mov_b32 m0, s28
	ds_read_b128 v[160:163], v151 offset:32768
	ds_read_b128 v[164:167], v151 offset:33792
	ds_read_b128 v[168:171], v151 offset:34816
	ds_read_b128 v[172:175], v151 offset:35840
	ds_read_b128 v[176:179], v151 offset:36864
	ds_read_b128 v[180:183], v151 offset:37888
	ds_read_b128 v[184:187], v151 offset:38912
	ds_read_b128 v[190:193], v151 offset:39936
	global_load_lds_dwordx4 v136, s[14:15]
	s_mov_b32 m0, s29
	s_nop 0
	global_load_lds_dwordx4 v132, s[14:15]
	s_waitcnt lgkmcnt(8)
	s_barrier
	s_waitcnt lgkmcnt(0)
	v_mfma_f32_16x16x32_bf16 v[126:129], v[142:145], v[160:163], v[126:129]
	v_mfma_f32_16x16x32_bf16 v[122:125], v[152:155], v[160:163], v[122:125]
	v_mfma_f32_16x16x32_bf16 v[110:113], v[142:145], v[168:171], v[110:113]
	v_mfma_f32_16x16x32_bf16 v[106:109], v[152:155], v[168:171], v[106:109]
	v_mfma_f32_16x16x32_bf16 v[94:97], v[142:145], v[176:179], v[94:97]
	v_mfma_f32_16x16x32_bf16 v[90:93], v[152:155], v[176:179], v[90:93]
	v_mfma_f32_16x16x32_bf16 v[78:81], v[142:145], v[184:187], v[78:81]
	v_mfma_f32_16x16x32_bf16 v[74:77], v[152:155], v[184:187], v[74:77]
	v_mfma_f32_16x16x32_bf16 v[126:129], v[146:149], v[164:167], v[126:129]
	v_mfma_f32_16x16x32_bf16 v[122:125], v[156:159], v[164:167], v[122:125]
	v_mfma_f32_16x16x32_bf16 v[110:113], v[146:149], v[172:175], v[110:113]
	v_mfma_f32_16x16x32_bf16 v[106:109], v[156:159], v[172:175], v[106:109]
	v_mfma_f32_16x16x32_bf16 v[94:97], v[146:149], v[180:183], v[94:97]
	v_mfma_f32_16x16x32_bf16 v[90:93], v[156:159], v[180:183], v[90:93]
	v_mfma_f32_16x16x32_bf16 v[78:81], v[146:149], v[190:193], v[78:81]
	v_mfma_f32_16x16x32_bf16 v[74:77], v[156:159], v[190:193], v[74:77]
	s_barrier
	s_add_i32 s14, 0, 0x1c000
	s_add_i32 s15, s86, s22
	v_add_u32_e32 v0, s14, v150
	s_mov_b32 m0, s15
	ds_read_b128 v[194:197], v0
	ds_read_b128 v[198:201], v0 offset:1024
	ds_read_b128 v[202:205], v0 offset:2048
	ds_read_b128 v[206:209], v0 offset:3072
	s_add_u32 s98, s12, s40
	s_addc_u32 s99, s13, s41
	global_load_lds_dwordx4 v134, s[98:99]
	s_add_i32 m0, s15, 0x2000
	s_add_u32 s98, s12, s40
	s_addc_u32 s99, s13, s41
	global_load_lds_dwordx4 v130, s[98:99]
	s_barrier
	s_waitcnt lgkmcnt(0)
	v_mfma_f32_16x16x32_bf16 v[118:121], v[194:197], v[160:163], v[118:121]
	v_mfma_f32_16x16x32_bf16 v[114:117], v[202:205], v[160:163], v[114:117]
	v_mfma_f32_16x16x32_bf16 v[102:105], v[194:197], v[168:171], v[102:105]
	v_mfma_f32_16x16x32_bf16 v[98:101], v[202:205], v[168:171], v[98:101]
	v_mfma_f32_16x16x32_bf16 v[86:89], v[194:197], v[176:179], v[86:89]
	v_mfma_f32_16x16x32_bf16 v[82:85], v[202:205], v[176:179], v[82:85]
	v_mfma_f32_16x16x32_bf16 v[70:73], v[194:197], v[184:187], v[70:73]
	v_mfma_f32_16x16x32_bf16 v[66:69], v[202:205], v[184:187], v[66:69]
	v_mfma_f32_16x16x32_bf16 v[118:121], v[198:201], v[164:167], v[118:121]
	v_mfma_f32_16x16x32_bf16 v[114:117], v[206:209], v[164:167], v[114:117]
	v_mfma_f32_16x16x32_bf16 v[102:105], v[198:201], v[172:175], v[102:105]
	v_mfma_f32_16x16x32_bf16 v[98:101], v[206:209], v[172:175], v[98:101]
	v_mfma_f32_16x16x32_bf16 v[86:89], v[198:201], v[180:183], v[86:89]
	v_mfma_f32_16x16x32_bf16 v[82:85], v[206:209], v[180:183], v[82:85]
	v_mfma_f32_16x16x32_bf16 v[70:73], v[198:201], v[190:193], v[70:73]
	v_mfma_f32_16x16x32_bf16 v[66:69], v[206:209], v[190:193], v[66:69]
	s_mov_b32 m0, s38
	v_lshl_add_u64 v[210:211], v[214:215], 0, s[40:41]
	s_barrier
	ds_read_b128 v[160:163], v151 offset:49152
	ds_read_b128 v[164:167], v151 offset:50176
	ds_read_b128 v[168:171], v151 offset:51200
	ds_read_b128 v[172:175], v151 offset:52224
	ds_read_b128 v[176:179], v151 offset:53248
	ds_read_b128 v[180:183], v151 offset:54272
	ds_read_b128 v[184:187], v151 offset:55296
	ds_read_b128 v[190:193], v151 offset:56320
	global_load_lds_dwordx4 v[210:211], off
	s_mov_b32 m0, s39
	v_lshl_add_u64 v[210:211], v[216:217], 0, s[40:41]
	global_load_lds_dwordx4 v[210:211], off
	s_waitcnt vmcnt(10)
	s_barrier
	s_waitcnt lgkmcnt(0)
	v_mfma_f32_16x16x32_bf16 v[62:65], v[142:145], v[160:163], v[62:65]
	v_mfma_f32_16x16x32_bf16 v[58:61], v[152:155], v[160:163], v[58:61]
	v_mfma_f32_16x16x32_bf16 v[46:49], v[142:145], v[168:171], v[46:49]
	v_mfma_f32_16x16x32_bf16 v[42:45], v[152:155], v[168:171], v[42:45]
	v_mfma_f32_16x16x32_bf16 v[30:33], v[142:145], v[176:179], v[30:33]
	v_mfma_f32_16x16x32_bf16 v[26:29], v[152:155], v[176:179], v[26:29]
	v_mfma_f32_16x16x32_bf16 v[14:17], v[142:145], v[184:187], v[14:17]
	v_mfma_f32_16x16x32_bf16 v[10:13], v[152:155], v[184:187], v[10:13]
	v_mfma_f32_16x16x32_bf16 v[62:65], v[146:149], v[164:167], v[62:65]
	v_mfma_f32_16x16x32_bf16 v[58:61], v[156:159], v[164:167], v[58:61]
	v_mfma_f32_16x16x32_bf16 v[46:49], v[146:149], v[172:175], v[46:49]
	v_mfma_f32_16x16x32_bf16 v[42:45], v[156:159], v[172:175], v[42:45]
	v_mfma_f32_16x16x32_bf16 v[30:33], v[146:149], v[180:183], v[30:33]
	v_mfma_f32_16x16x32_bf16 v[26:29], v[156:159], v[180:183], v[26:29]
	v_mfma_f32_16x16x32_bf16 v[14:17], v[146:149], v[190:193], v[14:17]
	v_mfma_f32_16x16x32_bf16 v[10:13], v[156:159], v[190:193], v[10:13]
	s_barrier
	s_add_u32 s12, s12, 0x40080
	s_addc_u32 s13, s13, 0
	s_add_i32 s14, s14, s22
	s_mov_b32 m0, s14
	s_nop 0
	global_load_lds_dwordx4 v134, s[12:13]
	s_add_i32 m0, s14, 0x2000
	s_nop 0
	global_load_lds_dwordx4 v130, s[12:13]
	s_add_i32 s86, 0, 0x10000
	v_add_u32_e32 v0, s86, v150
	ds_read_b128 v[142:145], v0
	ds_read_b128 v[146:149], v0 offset:1024
	ds_read_b128 v[152:155], v0 offset:2048
	ds_read_b128 v[156:159], v0 offset:3072
	s_waitcnt vmcnt(6)
	s_barrier
	v_mfma_f32_16x16x32_bf16 v[54:57], v[194:197], v[160:163], v[54:57]
	v_mfma_f32_16x16x32_bf16 v[50:53], v[202:205], v[160:163], v[50:53]
	v_mfma_f32_16x16x32_bf16 v[38:41], v[194:197], v[168:171], v[38:41]
	v_mfma_f32_16x16x32_bf16 v[34:37], v[202:205], v[168:171], v[34:37]
	v_mfma_f32_16x16x32_bf16 v[22:25], v[194:197], v[176:179], v[22:25]
	v_mfma_f32_16x16x32_bf16 v[18:21], v[202:205], v[176:179], v[18:21]
	v_mfma_f32_16x16x32_bf16 v[6:9], v[194:197], v[184:187], v[6:9]
	v_mfma_f32_16x16x32_bf16 v[2:5], v[202:205], v[184:187], v[2:5]
	v_mfma_f32_16x16x32_bf16 v[54:57], v[198:201], v[164:167], v[54:57]
	v_mfma_f32_16x16x32_bf16 v[50:53], v[206:209], v[164:167], v[50:53]
	v_mfma_f32_16x16x32_bf16 v[38:41], v[198:201], v[172:175], v[38:41]
	v_mfma_f32_16x16x32_bf16 v[34:37], v[206:209], v[172:175], v[34:37]
	v_mfma_f32_16x16x32_bf16 v[22:25], v[198:201], v[180:183], v[22:25]
	v_mfma_f32_16x16x32_bf16 v[18:21], v[206:209], v[180:183], v[18:21]
	v_mfma_f32_16x16x32_bf16 v[6:9], v[198:201], v[190:193], v[6:9]
	v_mfma_f32_16x16x32_bf16 v[2:5], v[206:209], v[190:193], v[2:5]
	s_add_i32 s85, s85, 2
	s_add_u32 s4, s4, 0x100
	s_addc_u32 s5, s5, 0
	s_add_u32 s78, s78, 0x100
	s_addc_u32 s79, s79, 0
	s_add_u32 s12, s4, 0xfffc0080
	s_addc_u32 s13, s5, -1
	s_cmp_eq_u32 s85, 12
	s_cselect_b32 s15, s44, s13
	s_cselect_b32 s14, s45, s12
	s_cselect_b32 s13, s47, s79
	s_cselect_b32 s12, s55, s78
	s_cmp_gt_u32 s85, 13
	s_barrier
	s_cbranch_scc0 .LBB0_267
	s_waitcnt lgkmcnt(0)
	v_mov_b32_e32 v156, v252
	s_mov_b64 s[4:5], -1
	v_and_b32_e32 v154, 63, v156
	s_andn2_b64 vcc, exec, s[2:3]
	v_lshlrev_b32_e32 v142, 2, v154
	s_cbranch_vccnz .LBB0_270
	v_lshlrev_b32_e32 v155, 2, v154
	s_mov_b64 s[4:5], 0

.LBB0_838:
	v_lshl_add_u64 v[178:179], s[88:89], 0, v[196:197]
	s_add_i32 m0, s39, 0xc000
	ds_read_b128 v[146:149], v213
	ds_read_b128 v[150:153], v213 offset:1024
	ds_read_b128 v[154:157], v213 offset:2048
	ds_read_b128 v[158:161], v213 offset:3072
	ds_read_b128 v[162:165], v213 offset:4096
	ds_read_b128 v[166:169], v213 offset:5120
	ds_read_b128 v[170:173], v213 offset:6144
	ds_read_b128 v[174:177], v213 offset:7168
	global_load_lds_dwordx4 v[178:179], off
	s_add_i32 m0, s39, 0xe000
	v_lshl_add_u64 v[178:179], s[88:89], 0, v[198:199]
	global_load_lds_dwordx4 v[178:179], off
	s_waitcnt lgkmcnt(8)
	s_barrier
	s_waitcnt lgkmcnt(0)
	v_mfma_f32_16x16x32_bf16 v[126:129], v[130:133], v[146:149], v[126:129]
	v_mfma_f32_16x16x32_bf16 v[122:125], v[138:141], v[146:149], v[122:125]
	v_mfma_f32_16x16x32_bf16 v[110:113], v[130:133], v[154:157], v[110:113]
	v_mfma_f32_16x16x32_bf16 v[106:109], v[138:141], v[154:157], v[106:109]
	v_mfma_f32_16x16x32_bf16 v[94:97], v[130:133], v[162:165], v[94:97]
	v_mfma_f32_16x16x32_bf16 v[90:93], v[138:141], v[162:165], v[90:93]
	v_mfma_f32_16x16x32_bf16 v[78:81], v[130:133], v[170:173], v[78:81]
	v_mfma_f32_16x16x32_bf16 v[74:77], v[138:141], v[170:173], v[74:77]
	v_mfma_f32_16x16x32_bf16 v[126:129], v[134:137], v[150:153], v[126:129]
	v_mfma_f32_16x16x32_bf16 v[122:125], v[142:145], v[150:153], v[122:125]
	v_mfma_f32_16x16x32_bf16 v[110:113], v[134:137], v[158:161], v[110:113]
	v_mfma_f32_16x16x32_bf16 v[106:109], v[142:145], v[158:161], v[106:109]
	v_mfma_f32_16x16x32_bf16 v[94:97], v[134:137], v[166:169], v[94:97]
	v_mfma_f32_16x16x32_bf16 v[90:93], v[142:145], v[166:169], v[90:93]
	v_mfma_f32_16x16x32_bf16 v[78:81], v[134:137], v[174:177], v[78:81]
	v_mfma_f32_16x16x32_bf16 v[74:77], v[142:145], v[174:177], v[74:77]
	s_barrier
	s_add_i32 s87, 0, 0x14000
	v_add_u32_e32 v186, s87, v212
	s_add_i32 s79, s79, s38
	ds_read_b128 v[178:181], v186
	ds_read_b128 v[182:185], v186 offset:1024
	ds_read_b128 v[200:203], v186 offset:2048
	ds_read_b128 v[204:207], v186 offset:3072
	s_mov_b32 m0, s79
	global_load_lds_dwordx4 v0, s[90:91]
	s_add_i32 m0, s79, 0x2000
	s_nop 0
	global_load_lds_dwordx4 v194, s[90:91]
	s_barrier
	s_waitcnt lgkmcnt(0)
	v_mfma_f32_16x16x32_bf16 v[118:121], v[178:181], v[146:149], v[118:121]
	v_mfma_f32_16x16x32_bf16 v[114:117], v[200:203], v[146:149], v[114:117]
	v_mfma_f32_16x16x32_bf16 v[102:105], v[178:181], v[154:157], v[102:105]
	v_mfma_f32_16x16x32_bf16 v[98:101], v[200:203], v[154:157], v[98:101]
	v_mfma_f32_16x16x32_bf16 v[86:89], v[178:181], v[162:165], v[86:89]
	v_mfma_f32_16x16x32_bf16 v[82:85], v[200:203], v[162:165], v[82:85]
	v_mfma_f32_16x16x32_bf16 v[70:73], v[178:181], v[170:173], v[70:73]
	v_mfma_f32_16x16x32_bf16 v[66:69], v[200:203], v[170:173], v[66:69]
	v_mfma_f32_16x16x32_bf16 v[118:121], v[182:185], v[150:153], v[118:121]
	v_mfma_f32_16x16x32_bf16 v[114:117], v[204:207], v[150:153], v[114:117]
	v_mfma_f32_16x16x32_bf16 v[102:105], v[182:185], v[158:161], v[102:105]
	v_mfma_f32_16x16x32_bf16 v[98:101], v[204:207], v[158:161], v[98:101]
	v_mfma_f32_16x16x32_bf16 v[86:89], v[182:185], v[166:169], v[86:89]
	v_mfma_f32_16x16x32_bf16 v[82:85], v[204:207], v[166:169], v[82:85]
	v_mfma_f32_16x16x32_bf16 v[70:73], v[182:185], v[174:177], v[70:73]
	v_mfma_f32_16x16x32_bf16 v[66:69], v[204:207], v[174:177], v[66:69]
	s_mov_b32 m0, s39
	s_barrier
	ds_read_b128 v[146:149], v213 offset:16384
	ds_read_b128 v[150:153], v213 offset:17408
	ds_read_b128 v[154:157], v213 offset:18432
	ds_read_b128 v[158:161], v213 offset:19456
	ds_read_b128 v[162:165], v213 offset:20480
	ds_read_b128 v[166:169], v213 offset:21504
	ds_read_b128 v[170:173], v213 offset:22528
	ds_read_b128 v[174:177], v213 offset:23552
	global_load_lds_dwordx4 v190, s[92:93]
	s_mov_b32 m0, s42
	s_nop 0
	global_load_lds_dwordx4 v192, s[92:93]
	s_waitcnt vmcnt(10)
	s_barrier
	s_waitcnt lgkmcnt(0)
	v_mfma_f32_16x16x32_bf16 v[62:65], v[130:133], v[146:149], v[62:65]
	v_mfma_f32_16x16x32_bf16 v[58:61], v[138:141], v[146:149], v[58:61]
	v_mfma_f32_16x16x32_bf16 v[46:49], v[130:133], v[154:157], v[46:49]
	v_mfma_f32_16x16x32_bf16 v[42:45], v[138:141], v[154:157], v[42:45]
	v_mfma_f32_16x16x32_bf16 v[30:33], v[130:133], v[162:165], v[30:33]
	v_mfma_f32_16x16x32_bf16 v[26:29], v[138:141], v[162:165], v[26:29]
	v_mfma_f32_16x16x32_bf16 v[14:17], v[130:133], v[170:173], v[14:17]
	v_mfma_f32_16x16x32_bf16 v[10:13], v[138:141], v[170:173], v[10:13]
	v_mfma_f32_16x16x32_bf16 v[62:65], v[134:137], v[150:153], v[62:65]
	v_mfma_f32_16x16x32_bf16 v[58:61], v[142:145], v[150:153], v[58:61]
	v_mfma_f32_16x16x32_bf16 v[46:49], v[134:137], v[158:161], v[46:49]
	v_mfma_f32_16x16x32_bf16 v[42:45], v[142:145], v[158:161], v[42:45]
	v_mfma_f32_16x16x32_bf16 v[30:33], v[134:137], v[166:169], v[30:33]
	v_mfma_f32_16x16x32_bf16 v[26:29], v[142:145], v[166:169], v[26:29]
	v_mfma_f32_16x16x32_bf16 v[14:17], v[134:137], v[174:177], v[14:17]
	v_mfma_f32_16x16x32_bf16 v[10:13], v[142:145], v[174:177], v[10:13]
	s_barrier
	s_add_u32 s88, s90, 0x40000
	s_addc_u32 s89, s91, 0
	s_add_i32 s79, s87, s38
	s_mov_b32 m0, s79
	s_nop 0
	global_load_lds_dwordx4 v0, s[88:89]
	s_add_i32 m0, s79, 0x2000
	s_nop 0
	global_load_lds_dwordx4 v194, s[88:89]
	s_add_i32 s79, 0, 0x18000
	v_add_u32_e32 v142, s79, v212
	ds_read_b128 v[130:133], v142
	ds_read_b128 v[134:137], v142 offset:1024
	ds_read_b128 v[138:141], v142 offset:2048
	ds_read_b128 v[142:145], v142 offset:3072
	s_waitcnt vmcnt(6)
	s_barrier
	v_mfma_f32_16x16x32_bf16 v[54:57], v[178:181], v[146:149], v[54:57]
	v_mfma_f32_16x16x32_bf16 v[50:53], v[200:203], v[146:149], v[50:53]
	v_mfma_f32_16x16x32_bf16 v[38:41], v[178:181], v[154:157], v[38:41]
	v_mfma_f32_16x16x32_bf16 v[34:37], v[200:203], v[154:157], v[34:37]
	v_mfma_f32_16x16x32_bf16 v[22:25], v[178:181], v[162:165], v[22:25]
	v_mfma_f32_16x16x32_bf16 v[18:21], v[200:203], v[162:165], v[18:21]
	v_mfma_f32_16x16x32_bf16 v[6:9], v[178:181], v[170:173], v[6:9]
	v_mfma_f32_16x16x32_bf16 v[2:5], v[200:203], v[170:173], v[2:5]
	v_mfma_f32_16x16x32_bf16 v[54:57], v[182:185], v[150:153], v[54:57]
	v_mfma_f32_16x16x32_bf16 v[50:53], v[204:207], v[150:153], v[50:53]
	v_mfma_f32_16x16x32_bf16 v[38:41], v[182:185], v[158:161], v[38:41]
	v_mfma_f32_16x16x32_bf16 v[34:37], v[204:207], v[158:161], v[34:37]
	v_mfma_f32_16x16x32_bf16 v[22:25], v[182:185], v[166:169], v[22:25]
	v_mfma_f32_16x16x32_bf16 v[18:21], v[204:207], v[166:169], v[18:21]
	v_mfma_f32_16x16x32_bf16 v[6:9], v[182:185], v[174:177], v[6:9]
	v_mfma_f32_16x16x32_bf16 v[2:5], v[204:207], v[174:177], v[2:5]
	s_barrier
	s_add_u32 s88, s92, 0xc0000
	s_addc_u32 s89, s93, 0
	s_mov_b32 m0, s43
	ds_read_b128 v[146:149], v213 offset:32768
	ds_read_b128 v[150:153], v213 offset:33792
	ds_read_b128 v[154:157], v213 offset:34816
	ds_read_b128 v[158:161], v213 offset:35840
	ds_read_b128 v[162:165], v213 offset:36864
	ds_read_b128 v[166:169], v213 offset:37888
	ds_read_b128 v[170:173], v213 offset:38912
	ds_read_b128 v[174:177], v213 offset:39936
	global_load_lds_dwordx4 v190, s[88:89]
	s_mov_b32 m0, s44
	s_nop 0
	global_load_lds_dwordx4 v192, s[88:89]
	s_waitcnt lgkmcnt(8)
	s_barrier
	s_waitcnt lgkmcnt(0)
	v_mfma_f32_16x16x32_bf16 v[126:129], v[130:133], v[146:149], v[126:129]
	v_mfma_f32_16x16x32_bf16 v[122:125], v[138:141], v[146:149], v[122:125]
	v_mfma_f32_16x16x32_bf16 v[110:113], v[130:133], v[154:157], v[110:113]
	v_mfma_f32_16x16x32_bf16 v[106:109], v[138:141], v[154:157], v[106:109]
	v_mfma_f32_16x16x32_bf16 v[94:97], v[130:133], v[162:165], v[94:97]
	v_mfma_f32_16x16x32_bf16 v[90:93], v[138:141], v[162:165], v[90:93]
	v_mfma_f32_16x16x32_bf16 v[78:81], v[130:133], v[170:173], v[78:81]
	v_mfma_f32_16x16x32_bf16 v[74:77], v[138:141], v[170:173], v[74:77]
	v_mfma_f32_16x16x32_bf16 v[126:129], v[134:137], v[150:153], v[126:129]
	v_mfma_f32_16x16x32_bf16 v[122:125], v[142:145], v[150:153], v[122:125]
	v_mfma_f32_16x16x32_bf16 v[110:113], v[134:137], v[158:161], v[110:113]
	v_mfma_f32_16x16x32_bf16 v[106:109], v[142:145], v[158:161], v[106:109]
	v_mfma_f32_16x16x32_bf16 v[94:97], v[134:137], v[166:169], v[94:97]
	v_mfma_f32_16x16x32_bf16 v[90:93], v[142:145], v[166:169], v[90:93]
	v_mfma_f32_16x16x32_bf16 v[78:81], v[134:137], v[174:177], v[78:81]
	v_mfma_f32_16x16x32_bf16 v[74:77], v[142:145], v[174:177], v[74:77]
	s_barrier
	s_add_i32 s87, 0, 0x1c000
	s_add_i32 s79, s79, s38
	v_add_u32_e32 v204, s87, v212
	s_mov_b32 m0, s79
	ds_read_b128 v[178:181], v204
	ds_read_b128 v[182:185], v204 offset:1024
	ds_read_b128 v[200:203], v204 offset:2048
	ds_read_b128 v[204:207], v204 offset:3072
	s_add_u32 s98, s90, s40
	s_addc_u32 s99, s91, s41
	global_load_lds_dwordx4 v0, s[98:99]
	s_add_i32 m0, s79, 0x2000
	s_add_u32 s98, s90, s40
	s_addc_u32 s99, s91, s41
	global_load_lds_dwordx4 v194, s[98:99]
	s_barrier
	s_waitcnt lgkmcnt(0)
	v_mfma_f32_16x16x32_bf16 v[118:121], v[178:181], v[146:149], v[118:121]
	v_mfma_f32_16x16x32_bf16 v[114:117], v[200:203], v[146:149], v[114:117]
	v_mfma_f32_16x16x32_bf16 v[102:105], v[178:181], v[154:157], v[102:105]
	v_mfma_f32_16x16x32_bf16 v[98:101], v[200:203], v[154:157], v[98:101]
	v_mfma_f32_16x16x32_bf16 v[86:89], v[178:181], v[162:165], v[86:89]
	v_mfma_f32_16x16x32_bf16 v[82:85], v[200:203], v[162:165], v[82:85]
	v_mfma_f32_16x16x32_bf16 v[70:73], v[178:181], v[170:173], v[70:73]
	v_mfma_f32_16x16x32_bf16 v[66:69], v[200:203], v[170:173], v[66:69]
	v_mfma_f32_16x16x32_bf16 v[118:121], v[182:185], v[150:153], v[118:121]
	v_mfma_f32_16x16x32_bf16 v[114:117], v[204:207], v[150:153], v[114:117]
	v_mfma_f32_16x16x32_bf16 v[102:105], v[182:185], v[158:161], v[102:105]
	v_mfma_f32_16x16x32_bf16 v[98:101], v[204:207], v[158:161], v[98:101]
	v_mfma_f32_16x16x32_bf16 v[86:89], v[182:185], v[166:169], v[86:89]
	v_mfma_f32_16x16x32_bf16 v[82:85], v[204:207], v[166:169], v[82:85]
	v_mfma_f32_16x16x32_bf16 v[70:73], v[182:185], v[174:177], v[70:73]
	v_mfma_f32_16x16x32_bf16 v[66:69], v[204:207], v[174:177], v[66:69]
	s_mov_b32 m0, s60
	s_barrier
	ds_read_b128 v[146:149], v213 offset:49152
	ds_read_b128 v[150:153], v213 offset:50176
	ds_read_b128 v[154:157], v213 offset:51200
	ds_read_b128 v[158:161], v213 offset:52224
	ds_read_b128 v[162:165], v213 offset:53248
	ds_read_b128 v[166:169], v213 offset:54272
	ds_read_b128 v[170:173], v213 offset:55296
	ds_read_b128 v[174:177], v213 offset:56320
	s_add_u32 s98, s92, s40
	s_addc_u32 s99, s93, s41
	global_load_lds_dwordx4 v190, s[98:99]
	s_mov_b32 m0, s61
	s_add_u32 s98, s92, s40
	s_addc_u32 s99, s93, s41
	global_load_lds_dwordx4 v192, s[98:99]
	s_waitcnt vmcnt(10)
	s_barrier
	s_waitcnt lgkmcnt(0)
	v_mfma_f32_16x16x32_bf16 v[62:65], v[130:133], v[146:149], v[62:65]
	v_mfma_f32_16x16x32_bf16 v[58:61], v[138:141], v[146:149], v[58:61]
	v_mfma_f32_16x16x32_bf16 v[46:49], v[130:133], v[154:157], v[46:49]
	v_mfma_f32_16x16x32_bf16 v[42:45], v[138:141], v[154:157], v[42:45]
	v_mfma_f32_16x16x32_bf16 v[30:33], v[130:133], v[162:165], v[30:33]
	v_mfma_f32_16x16x32_bf16 v[26:29], v[138:141], v[162:165], v[26:29]
	v_mfma_f32_16x16x32_bf16 v[14:17], v[130:133], v[170:173], v[14:17]
	v_mfma_f32_16x16x32_bf16 v[10:13], v[138:141], v[170:173], v[10:13]
	v_mfma_f32_16x16x32_bf16 v[62:65], v[134:137], v[150:153], v[62:65]
	v_mfma_f32_16x16x32_bf16 v[58:61], v[142:145], v[150:153], v[58:61]
	v_mfma_f32_16x16x32_bf16 v[46:49], v[134:137], v[158:161], v[46:49]
	v_mfma_f32_16x16x32_bf16 v[42:45], v[142:145], v[158:161], v[42:45]
	v_mfma_f32_16x16x32_bf16 v[30:33], v[134:137], v[166:169], v[30:33]
	v_mfma_f32_16x16x32_bf16 v[26:29], v[142:145], v[166:169], v[26:29]
	v_mfma_f32_16x16x32_bf16 v[14:17], v[134:137], v[174:177], v[14:17]
	v_mfma_f32_16x16x32_bf16 v[10:13], v[142:145], v[174:177], v[10:13]
	s_barrier
	s_add_u32 s88, s90, 0x40080
	s_addc_u32 s89, s91, 0
	s_add_i32 s79, s87, s38
	s_mov_b32 m0, s79
	s_nop 0
	global_load_lds_dwordx4 v0, s[88:89]
	s_add_i32 m0, s79, 0x2000
	s_nop 0
	global_load_lds_dwordx4 v194, s[88:89]
	s_add_i32 s79, 0, 0x10000
	v_add_u32_e32 v142, s79, v212
	ds_read_b128 v[130:133], v142
	ds_read_b128 v[134:137], v142 offset:1024
	ds_read_b128 v[138:141], v142 offset:2048
	ds_read_b128 v[142:145], v142 offset:3072
	s_waitcnt vmcnt(6)
	s_barrier
	v_mfma_f32_16x16x32_bf16 v[54:57], v[178:181], v[146:149], v[54:57]
	v_mfma_f32_16x16x32_bf16 v[50:53], v[200:203], v[146:149], v[50:53]
	v_mfma_f32_16x16x32_bf16 v[38:41], v[178:181], v[154:157], v[38:41]
	v_mfma_f32_16x16x32_bf16 v[34:37], v[200:203], v[154:157], v[34:37]
	v_mfma_f32_16x16x32_bf16 v[22:25], v[178:181], v[162:165], v[22:25]
	v_mfma_f32_16x16x32_bf16 v[18:21], v[200:203], v[162:165], v[18:21]
	v_mfma_f32_16x16x32_bf16 v[6:9], v[178:181], v[170:173], v[6:9]
	v_mfma_f32_16x16x32_bf16 v[2:5], v[200:203], v[170:173], v[2:5]
	v_mfma_f32_16x16x32_bf16 v[54:57], v[182:185], v[150:153], v[54:57]
	v_mfma_f32_16x16x32_bf16 v[50:53], v[204:207], v[150:153], v[50:53]
	v_mfma_f32_16x16x32_bf16 v[38:41], v[182:185], v[158:161], v[38:41]
	v_mfma_f32_16x16x32_bf16 v[34:37], v[204:207], v[158:161], v[34:37]
	v_mfma_f32_16x16x32_bf16 v[22:25], v[182:185], v[166:169], v[22:25]
	v_mfma_f32_16x16x32_bf16 v[18:21], v[204:207], v[166:169], v[18:21]
	v_mfma_f32_16x16x32_bf16 v[6:9], v[182:185], v[174:177], v[6:9]
	v_mfma_f32_16x16x32_bf16 v[2:5], v[204:207], v[174:177], v[2:5]
	s_add_i32 s78, s78, 2
	s_add_u32 s34, s34, 0x100
	s_addc_u32 s75, s75, 0
	s_mov_b64 s[88:89], s[4:5]
	s_add_u32 s4, s88, 0x100
	s_addc_u32 s5, s89, 0
	s_cmp_eq_u32 s78, 12
	s_cselect_b32 s93, s17, s5
	s_cselect_b32 s92, s16, s4
	s_cselect_b32 s91, s15, s75
	s_cselect_b32 s90, s23, s34
	s_cmp_gt_u32 s78, 13
	s_barrier
	s_cbranch_scc0 .LBB0_838
	s_waitcnt lgkmcnt(0)
	s_lshl_b32 s4, s22, 8
	v_mov_b32_e32 v186, v252
	s_add_i32 s4, s4, s47
	s_nop 0
	v_and_or_b32 v202, v186, 15, s4
	s_lshl_b32 s4, s86, 8
	s_or_b32 s4, s4, s55
	v_lshrrev_b32_e32 v130, 1, v186
	v_and_or_b32 v200, v130, 24, s4
	v_ashrrev_i32_e32 v201, 31, v200
	v_ashrrev_i32_e32 v203, 31, v202
	v_lshl_add_u64 v[204:205], v[200:201], 2, s[6:7]
	v_lshlrev_b64 v[130:131], 12, v[202:203]
	v_lshl_add_u64 v[130:131], v[204:205], 0, v[130:131]
	global_load_dwordx4 v[216:219], v[130:131], off offset:16
	global_load_dwordx4 v[220:223], v[130:131], off
	global_load_dwordx4 v[178:181], v[130:131], off offset:528
	global_load_dwordx4 v[182:185], v[130:131], off offset:512
	v_or_b32_e32 v210, 16, v202
	v_ashrrev_i32_e32 v211, 31, v210
	v_lshlrev_b64 v[130:131], 12, v[210:211]
	v_or_b32_e32 v208, 32, v202
	v_lshl_add_u64 v[130:131], v[204:205], 0, v[130:131]
	v_ashrrev_i32_e32 v209, 31, v208
	global_load_dwordx4 v[170:173], v[130:131], off offset:16
	global_load_dwordx4 v[174:177], v[130:131], off
	global_load_dwordx4 v[162:165], v[130:131], off offset:528
	global_load_dwordx4 v[166:169], v[130:131], off offset:512
	v_lshlrev_b64 v[130:131], 12, v[208:209]
	v_or_b32_e32 v206, 48, v202
	v_lshl_add_u64 v[130:131], v[204:205], 0, v[130:131]
	v_ashrrev_i32_e32 v207, 31, v206
	global_load_dwordx4 v[154:157], v[130:131], off offset:16
	global_load_dwordx4 v[158:161], v[130:131], off
	global_load_dwordx4 v[138:141], v[130:131], off offset:528
	global_load_dwordx4 v[142:145], v[130:131], off offset:512
	v_lshlrev_b64 v[130:131], 12, v[206:207]
	v_lshl_add_u64 v[134:135], v[204:205], 0, v[130:131]
	global_load_dwordx4 v[146:149], v[134:135], off offset:16
	global_load_dwordx4 v[150:153], v[134:135], off
	global_load_dwordx4 v[130:133], v[134:135], off offset:528
	s_nop 0
	global_load_dwordx4 v[134:137], v[134:135], off offset:512
	v_and_b32_e32 v186, 63, v186
	v_lshlrev_b32_e32 v187, 2, v186
	v_xor_b32_e32 v215, 64, v187
	v_xor_b32_e32 v214, 0x80, v187
	v_cmp_gt_u32_e32 vcc, 16, v186
	v_lshlrev_b64 v[186:187], 10, v[202:203]
	v_lshl_add_u64 v[186:187], v[186:187], 0, v[200:201]
	s_lshl_b32 s4, s86, 2
	s_ashr_i32 s5, s4, 31
	s_waitcnt vmcnt(0)
	v_pk_add_f32 v[124:125], v[124:125], v[218:219]
	v_pk_add_f32 v[128:129], v[128:129], v[222:223]
	v_pk_add_f32 v[126:127], v[126:127], v[220:221]
	v_pk_mul_f32 v[218:219], v[128:129], v[128:129]
	v_pk_mul_f32 v[220:221], v[126:127], v[126:127]
	v_pk_add_f32 v[122:123], v[122:123], v[216:217]
	v_lshl_add_u64 v[216:217], v[186:187], 2, s[12:13]
	v_add_f32_e32 v220, v220, v221
	v_add_f32_e32 v218, v218, v219
	global_store_dwordx4 v[216:217], v[126:129], off
	global_store_dwordx4 v[216:217], v[122:125], off offset:16
	v_add_f32_e32 v222, v220, v218
	v_pk_mul_f32 v[220:221], v[122:123], v[122:123]
	v_cvt_pk_bf16_f32 v126, v126, v127
	v_cvt_pk_bf16_f32 v127, v128, v129
	v_cvt_pk_bf16_f32 v128, v122, v123
	v_cvt_pk_bf16_f32 v129, v124, v125
	v_lshl_add_u64 v[122:123], v[186:187], 1, s[8:9]
	v_pk_add_f32 v[120:121], v[120:121], v[184:185]
	v_pk_add_f32 v[118:119], v[118:119], v[182:183]
	v_pk_mul_f32 v[218:219], v[124:125], v[124:125]
	global_store_dwordx4 v[122:123], v[126:129], off
	v_pk_mul_f32 v[124:125], v[120:121], v[120:121]
	v_pk_add_f32 v[116:117], v[116:117], v[180:181]
	v_pk_mul_f32 v[126:127], v[118:119], v[118:119]
	v_pk_add_f32 v[114:115], v[114:115], v[178:179]
	v_add_f32_e32 v126, v126, v127
	v_add_f32_e32 v124, v124, v125
	v_add_f32_e32 v128, v126, v124
	v_pk_mul_f32 v[124:125], v[116:117], v[116:117]
	v_pk_mul_f32 v[126:127], v[114:115], v[114:115]
	v_add_f32_e32 v220, v220, v221
	v_add_f32_e32 v218, v218, v219
	v_add_f32_e32 v126, v126, v127
	v_add_f32_e32 v124, v124, v125
	v_add_f32_e32 v218, v220, v218
	v_add_f32_e32 v124, v126, v124
	v_add_f32_e32 v218, v222, v218
	v_add_f32_e32 v124, v128, v124
	v_add_f32_e32 v124, v218, v124
	global_store_dwordx4 v[216:217], v[118:121], off offset:512
	global_store_dwordx4 v[216:217], v[114:117], off offset:528
	s_nop 0
	v_cvt_pk_bf16_f32 v118, v118, v119
	v_cvt_pk_bf16_f32 v119, v120, v121
	v_cvt_pk_bf16_f32 v120, v114, v115
	ds_bpermute_b32 v114, v215, v124
	v_cvt_pk_bf16_f32 v121, v116, v117
	global_store_dwordx4 v[122:123], v[118:121], off offset:256
	s_waitcnt lgkmcnt(0)
	v_add_f32_e32 v114, v124, v114
	ds_bpermute_b32 v115, v214, v114
	s_and_saveexec_b64 s[22:23], vcc
	s_cbranch_execz .LBB0_841
	v_lshlrev_b64 v[116:117], 6, v[202:203]
	v_lshl_add_u64 v[116:117], s[10:11], 0, v[116:117]
	v_lshl_add_u64 v[116:117], s[4:5], 2, v[116:117]
	s_lshl_b32 s34, s45, 2
	v_lshl_add_u64 v[116:117], v[116:117], 0, s[34:35]
	s_waitcnt lgkmcnt(0)
	v_add_f32_e32 v114, v114, v115
	global_store_dword v[116:117], v114, off

.LBB0_919:
	v_lshl_add_u64 v[154:155], s[6:7], 0, v[164:165]
	s_add_i32 m0, s43, 0xc000
	ds_read_b128 v[146:149], v253
	ds_read_b128 v[150:153], v253 offset:1024
	ds_read_b128 v[168:171], v253 offset:2048
	ds_read_b128 v[172:175], v253 offset:3072
	ds_read_b128 v[176:179], v253 offset:4096
	ds_read_b128 v[180:183], v253 offset:5120
	ds_read_b128 v[184:187], v253 offset:6144
	ds_read_b128 v[190:193], v253 offset:7168
	global_load_lds_dwordx4 v[154:155], off
	s_add_i32 m0, s43, 0xe000
	v_lshl_add_u64 v[154:155], s[6:7], 0, v[166:167]
	global_load_lds_dwordx4 v[154:155], off
	s_waitcnt lgkmcnt(8)
	s_barrier
	s_waitcnt lgkmcnt(0)
	v_mfma_f32_16x16x32_bf16 v[126:129], v[130:133], v[146:149], v[126:129]
	v_mfma_f32_16x16x32_bf16 v[70:73], v[138:141], v[146:149], v[70:73]
	v_mfma_f32_16x16x32_bf16 v[122:125], v[130:133], v[168:171], v[122:125]
	v_mfma_f32_16x16x32_bf16 v[74:77], v[138:141], v[168:171], v[74:77]
	v_mfma_f32_16x16x32_bf16 v[114:117], v[130:133], v[176:179], v[114:117]
	v_mfma_f32_16x16x32_bf16 v[66:69], v[138:141], v[176:179], v[66:69]
	v_mfma_f32_16x16x32_bf16 v[110:113], v[130:133], v[184:187], v[110:113]
	v_mfma_f32_16x16x32_bf16 v[78:81], v[138:141], v[184:187], v[78:81]
	v_mfma_f32_16x16x32_bf16 v[126:129], v[134:137], v[150:153], v[126:129]
	v_mfma_f32_16x16x32_bf16 v[70:73], v[142:145], v[150:153], v[70:73]
	v_mfma_f32_16x16x32_bf16 v[122:125], v[134:137], v[172:175], v[122:125]
	v_mfma_f32_16x16x32_bf16 v[74:77], v[142:145], v[172:175], v[74:77]
	v_mfma_f32_16x16x32_bf16 v[114:117], v[134:137], v[180:183], v[114:117]
	v_mfma_f32_16x16x32_bf16 v[66:69], v[142:145], v[180:183], v[66:69]
	v_mfma_f32_16x16x32_bf16 v[110:113], v[134:137], v[190:193], v[110:113]
	v_mfma_f32_16x16x32_bf16 v[78:81], v[142:145], v[190:193], v[78:81]
	s_barrier
	s_add_i32 vcc_hi, 0, 0x14000
	s_add_i32 s6, vcc_lo, s39
	v_add_u32_e32 v0, vcc_hi, v254
	s_mov_b32 m0, s6
	ds_read_b128 v[194:197], v0
	ds_read_b128 v[198:201], v0 offset:1024
	ds_read_b128 v[202:205], v0 offset:2048
	ds_read_b128 v[206:209], v0 offset:3072
	global_load_lds_dwordx4 v160, s[90:91]
	s_add_i32 m0, s6, 0x2000
	s_nop 0
	global_load_lds_dwordx4 v156, s[90:91]
	s_barrier
	s_waitcnt lgkmcnt(0)
	v_mfma_f32_16x16x32_bf16 v[118:121], v[194:197], v[146:149], v[118:121]
	v_mfma_f32_16x16x32_bf16 v[94:97], v[202:205], v[146:149], v[94:97]
	v_mfma_f32_16x16x32_bf16 v[106:109], v[194:197], v[168:171], v[106:109]
	v_mfma_f32_16x16x32_bf16 v[90:93], v[202:205], v[168:171], v[90:93]
	v_mfma_f32_16x16x32_bf16 v[102:105], v[194:197], v[176:179], v[102:105]
	v_mfma_f32_16x16x32_bf16 v[82:85], v[202:205], v[176:179], v[82:85]
	v_mfma_f32_16x16x32_bf16 v[98:101], v[194:197], v[184:187], v[98:101]
	v_mfma_f32_16x16x32_bf16 v[86:89], v[202:205], v[184:187], v[86:89]
	v_mfma_f32_16x16x32_bf16 v[118:121], v[198:201], v[150:153], v[118:121]
	v_mfma_f32_16x16x32_bf16 v[94:97], v[206:209], v[150:153], v[94:97]
	v_mfma_f32_16x16x32_bf16 v[106:109], v[198:201], v[172:175], v[106:109]
	v_mfma_f32_16x16x32_bf16 v[90:93], v[206:209], v[172:175], v[90:93]
	v_mfma_f32_16x16x32_bf16 v[102:105], v[198:201], v[180:183], v[102:105]
	v_mfma_f32_16x16x32_bf16 v[82:85], v[206:209], v[180:183], v[82:85]
	v_mfma_f32_16x16x32_bf16 v[98:101], v[198:201], v[190:193], v[98:101]
	v_mfma_f32_16x16x32_bf16 v[86:89], v[206:209], v[190:193], v[86:89]
	s_mov_b32 m0, s43
	v_lshl_add_u64 v[212:213], s[92:93], 0, v[162:163]
	s_barrier
	ds_read_b128 v[146:149], v253 offset:16384
	ds_read_b128 v[150:153], v253 offset:17408
	ds_read_b128 v[168:171], v253 offset:18432
	ds_read_b128 v[172:175], v253 offset:19456
	ds_read_b128 v[176:179], v253 offset:20480
	ds_read_b128 v[180:183], v253 offset:21504
	ds_read_b128 v[184:187], v253 offset:22528
	ds_read_b128 v[190:193], v253 offset:23552
	global_load_lds_dwordx4 v[212:213], off
	s_mov_b32 m0, s60
	v_lshl_add_u64 v[214:215], s[92:93], 0, v[158:159]
	global_load_lds_dwordx4 v[214:215], off
	s_waitcnt vmcnt(10)
	s_barrier
	s_waitcnt lgkmcnt(0)
	v_mfma_f32_16x16x32_bf16 v[62:65], v[130:133], v[146:149], v[62:65]
	v_mfma_f32_16x16x32_bf16 v[10:13], v[138:141], v[146:149], v[10:13]
	v_mfma_f32_16x16x32_bf16 v[58:61], v[130:133], v[168:171], v[58:61]
	v_mfma_f32_16x16x32_bf16 v[14:17], v[138:141], v[168:171], v[14:17]
	v_mfma_f32_16x16x32_bf16 v[54:57], v[130:133], v[176:179], v[54:57]
	v_mfma_f32_16x16x32_bf16 v[6:9], v[138:141], v[176:179], v[6:9]
	v_mfma_f32_16x16x32_bf16 v[42:45], v[130:133], v[184:187], v[42:45]
	v_mfma_f32_16x16x32_bf16 v[2:5], v[138:141], v[184:187], v[2:5]
	v_mfma_f32_16x16x32_bf16 v[62:65], v[134:137], v[150:153], v[62:65]
	v_mfma_f32_16x16x32_bf16 v[10:13], v[142:145], v[150:153], v[10:13]
	v_mfma_f32_16x16x32_bf16 v[58:61], v[134:137], v[172:175], v[58:61]
	v_mfma_f32_16x16x32_bf16 v[14:17], v[142:145], v[172:175], v[14:17]
	v_mfma_f32_16x16x32_bf16 v[54:57], v[134:137], v[180:183], v[54:57]
	v_mfma_f32_16x16x32_bf16 v[6:9], v[142:145], v[180:183], v[6:9]
	v_mfma_f32_16x16x32_bf16 v[42:45], v[134:137], v[190:193], v[42:45]
	v_mfma_f32_16x16x32_bf16 v[2:5], v[142:145], v[190:193], v[2:5]
	s_barrier
	s_add_u32 s6, s90, 0x40000
	s_addc_u32 s7, s91, 0
	s_add_i32 vcc_lo, vcc_hi, s39
	s_mov_b32 m0, vcc_lo
	s_nop 0
	global_load_lds_dwordx4 v160, s[6:7]
	s_add_i32 m0, vcc_lo, 0x2000
	s_nop 0
	global_load_lds_dwordx4 v156, s[6:7]
	s_add_i32 vcc_lo, 0, 0x18000
	v_add_u32_e32 v0, vcc_lo, v254
	ds_read_b128 v[130:133], v0
	ds_read_b128 v[134:137], v0 offset:1024
	ds_read_b128 v[138:141], v0 offset:2048
	ds_read_b128 v[142:145], v0 offset:3072
	s_waitcnt vmcnt(6)
	s_barrier
	v_mfma_f32_16x16x32_bf16 v[50:53], v[194:197], v[146:149], v[50:53]
	v_mfma_f32_16x16x32_bf16 v[26:29], v[202:205], v[146:149], v[26:29]
	v_mfma_f32_16x16x32_bf16 v[46:49], v[194:197], v[168:171], v[46:49]
	v_mfma_f32_16x16x32_bf16 v[30:33], v[202:205], v[168:171], v[30:33]
	v_mfma_f32_16x16x32_bf16 v[38:41], v[194:197], v[176:179], v[38:41]
	v_mfma_f32_16x16x32_bf16 v[22:25], v[202:205], v[176:179], v[22:25]
	v_mfma_f32_16x16x32_bf16 v[34:37], v[194:197], v[184:187], v[34:37]
	v_mfma_f32_16x16x32_bf16 v[18:21], v[202:205], v[184:187], v[18:21]
	v_mfma_f32_16x16x32_bf16 v[50:53], v[198:201], v[150:153], v[50:53]
	v_mfma_f32_16x16x32_bf16 v[26:29], v[206:209], v[150:153], v[26:29]
	v_mfma_f32_16x16x32_bf16 v[46:49], v[198:201], v[172:175], v[46:49]
	v_mfma_f32_16x16x32_bf16 v[30:33], v[206:209], v[172:175], v[30:33]
	v_mfma_f32_16x16x32_bf16 v[38:41], v[198:201], v[180:183], v[38:41]
	v_mfma_f32_16x16x32_bf16 v[22:25], v[206:209], v[180:183], v[22:25]
	v_mfma_f32_16x16x32_bf16 v[34:37], v[198:201], v[190:193], v[34:37]
	v_mfma_f32_16x16x32_bf16 v[18:21], v[206:209], v[190:193], v[18:21]
	s_barrier
	s_add_u32 s6, s92, 0x40000
	s_addc_u32 s7, s93, 0
	s_mov_b32 m0, s61
	ds_read_b128 v[146:149], v253 offset:32768
	ds_read_b128 v[150:153], v253 offset:33792
	ds_read_b128 v[168:171], v253 offset:34816
	ds_read_b128 v[172:175], v253 offset:35840
	ds_read_b128 v[176:179], v253 offset:36864
	ds_read_b128 v[180:183], v253 offset:37888
	ds_read_b128 v[184:187], v253 offset:38912
	ds_read_b128 v[190:193], v253 offset:39936
	global_load_lds_dwordx4 v162, s[6:7]
	s_mov_b32 m0, s72
	s_nop 0
	global_load_lds_dwordx4 v158, s[6:7]
	s_waitcnt lgkmcnt(8)
	s_barrier
	s_waitcnt lgkmcnt(0)
	v_mfma_f32_16x16x32_bf16 v[126:129], v[130:133], v[146:149], v[126:129]
	v_mfma_f32_16x16x32_bf16 v[70:73], v[138:141], v[146:149], v[70:73]
	v_mfma_f32_16x16x32_bf16 v[122:125], v[130:133], v[168:171], v[122:125]
	v_mfma_f32_16x16x32_bf16 v[74:77], v[138:141], v[168:171], v[74:77]
	v_mfma_f32_16x16x32_bf16 v[114:117], v[130:133], v[176:179], v[114:117]
	v_mfma_f32_16x16x32_bf16 v[66:69], v[138:141], v[176:179], v[66:69]
	v_mfma_f32_16x16x32_bf16 v[110:113], v[130:133], v[184:187], v[110:113]
	v_mfma_f32_16x16x32_bf16 v[78:81], v[138:141], v[184:187], v[78:81]
	v_mfma_f32_16x16x32_bf16 v[126:129], v[134:137], v[150:153], v[126:129]
	v_mfma_f32_16x16x32_bf16 v[70:73], v[142:145], v[150:153], v[70:73]
	v_mfma_f32_16x16x32_bf16 v[122:125], v[134:137], v[172:175], v[122:125]
	v_mfma_f32_16x16x32_bf16 v[74:77], v[142:145], v[172:175], v[74:77]
	v_mfma_f32_16x16x32_bf16 v[114:117], v[134:137], v[180:183], v[114:117]
	v_mfma_f32_16x16x32_bf16 v[66:69], v[142:145], v[180:183], v[66:69]
	v_mfma_f32_16x16x32_bf16 v[110:113], v[134:137], v[190:193], v[110:113]
	v_mfma_f32_16x16x32_bf16 v[78:81], v[142:145], v[190:193], v[78:81]
	s_barrier
	s_add_i32 s92, 0, 0x1c000
	s_add_i32 s6, vcc_lo, s39
	v_add_u32_e32 v0, s92, v254
	s_mov_b32 m0, s6
	ds_read_b128 v[194:197], v0
	ds_read_b128 v[198:201], v0 offset:1024
	ds_read_b128 v[202:205], v0 offset:2048
	ds_read_b128 v[206:209], v0 offset:3072
	s_add_u32 s98, s90, s40
	s_addc_u32 s99, s91, s41
	global_load_lds_dwordx4 v160, s[98:99]
	s_add_i32 m0, s6, 0x2000
	s_add_u32 s98, s90, s40
	s_addc_u32 s99, s91, s41
	global_load_lds_dwordx4 v156, s[98:99]
	s_barrier
	s_waitcnt lgkmcnt(0)
	v_mfma_f32_16x16x32_bf16 v[118:121], v[194:197], v[146:149], v[118:121]
	v_mfma_f32_16x16x32_bf16 v[94:97], v[202:205], v[146:149], v[94:97]
	v_mfma_f32_16x16x32_bf16 v[106:109], v[194:197], v[168:171], v[106:109]
	v_mfma_f32_16x16x32_bf16 v[90:93], v[202:205], v[168:171], v[90:93]
	v_mfma_f32_16x16x32_bf16 v[102:105], v[194:197], v[176:179], v[102:105]
	v_mfma_f32_16x16x32_bf16 v[82:85], v[202:205], v[176:179], v[82:85]
	v_mfma_f32_16x16x32_bf16 v[98:101], v[194:197], v[184:187], v[98:101]
	v_mfma_f32_16x16x32_bf16 v[86:89], v[202:205], v[184:187], v[86:89]
	v_mfma_f32_16x16x32_bf16 v[118:121], v[198:201], v[150:153], v[118:121]
	v_mfma_f32_16x16x32_bf16 v[94:97], v[206:209], v[150:153], v[94:97]
	v_mfma_f32_16x16x32_bf16 v[106:109], v[198:201], v[172:175], v[106:109]
	v_mfma_f32_16x16x32_bf16 v[90:93], v[206:209], v[172:175], v[90:93]
	v_mfma_f32_16x16x32_bf16 v[102:105], v[198:201], v[180:183], v[102:105]
	v_mfma_f32_16x16x32_bf16 v[82:85], v[206:209], v[180:183], v[82:85]
	v_mfma_f32_16x16x32_bf16 v[98:101], v[198:201], v[190:193], v[98:101]
	v_mfma_f32_16x16x32_bf16 v[86:89], v[206:209], v[190:193], v[86:89]
	s_mov_b32 m0, s95
	v_lshl_add_u64 v[154:155], v[212:213], 0, s[40:41]
	s_barrier
	ds_read_b128 v[146:149], v253 offset:49152
	ds_read_b128 v[150:153], v253 offset:50176
	ds_read_b128 v[168:171], v253 offset:51200
	ds_read_b128 v[172:175], v253 offset:52224
	ds_read_b128 v[176:179], v253 offset:53248
	ds_read_b128 v[180:183], v253 offset:54272
	ds_read_b128 v[184:187], v253 offset:55296
	ds_read_b128 v[190:193], v253 offset:56320
	global_load_lds_dwordx4 v[154:155], off
	s_mov_b32 m0, s96
	v_lshl_add_u64 v[154:155], v[214:215], 0, s[40:41]
	global_load_lds_dwordx4 v[154:155], off
	s_waitcnt vmcnt(10)
	s_barrier
	s_waitcnt lgkmcnt(0)
	v_mfma_f32_16x16x32_bf16 v[62:65], v[130:133], v[146:149], v[62:65]
	v_mfma_f32_16x16x32_bf16 v[10:13], v[138:141], v[146:149], v[10:13]
	v_mfma_f32_16x16x32_bf16 v[58:61], v[130:133], v[168:171], v[58:61]
	v_mfma_f32_16x16x32_bf16 v[14:17], v[138:141], v[168:171], v[14:17]
	v_mfma_f32_16x16x32_bf16 v[54:57], v[130:133], v[176:179], v[54:57]
	v_mfma_f32_16x16x32_bf16 v[6:9], v[138:141], v[176:179], v[6:9]
	v_mfma_f32_16x16x32_bf16 v[42:45], v[130:133], v[184:187], v[42:45]
	v_mfma_f32_16x16x32_bf16 v[2:5], v[138:141], v[184:187], v[2:5]
	v_mfma_f32_16x16x32_bf16 v[62:65], v[134:137], v[150:153], v[62:65]
	v_mfma_f32_16x16x32_bf16 v[10:13], v[142:145], v[150:153], v[10:13]
	v_mfma_f32_16x16x32_bf16 v[58:61], v[134:137], v[172:175], v[58:61]
	v_mfma_f32_16x16x32_bf16 v[14:17], v[142:145], v[172:175], v[14:17]
	v_mfma_f32_16x16x32_bf16 v[54:57], v[134:137], v[180:183], v[54:57]
	v_mfma_f32_16x16x32_bf16 v[6:9], v[142:145], v[180:183], v[6:9]
	v_mfma_f32_16x16x32_bf16 v[42:45], v[134:137], v[190:193], v[42:45]
	v_mfma_f32_16x16x32_bf16 v[2:5], v[142:145], v[190:193], v[2:5]
	s_barrier
	s_add_u32 s6, s90, 0x40080
	s_addc_u32 s7, s91, 0
	s_add_i32 s90, s92, s39
	s_mov_b32 m0, s90
	s_nop 0
	global_load_lds_dwordx4 v160, s[6:7]
	s_add_i32 m0, s90, 0x2000
	s_nop 0
	global_load_lds_dwordx4 v156, s[6:7]
	s_add_i32 vcc_lo, 0, 0x10000
	v_add_u32_e32 v0, vcc_lo, v254
	ds_read_b128 v[130:133], v0
	ds_read_b128 v[134:137], v0 offset:1024
	ds_read_b128 v[138:141], v0 offset:2048
	ds_read_b128 v[142:145], v0 offset:3072
	s_waitcnt vmcnt(6)
	s_barrier
	v_mfma_f32_16x16x32_bf16 v[50:53], v[194:197], v[146:149], v[50:53]
	v_mfma_f32_16x16x32_bf16 v[26:29], v[202:205], v[146:149], v[26:29]
	v_mfma_f32_16x16x32_bf16 v[46:49], v[194:197], v[168:171], v[46:49]
	v_mfma_f32_16x16x32_bf16 v[30:33], v[202:205], v[168:171], v[30:33]
	v_mfma_f32_16x16x32_bf16 v[38:41], v[194:197], v[176:179], v[38:41]
	v_mfma_f32_16x16x32_bf16 v[22:25], v[202:205], v[176:179], v[22:25]
	v_mfma_f32_16x16x32_bf16 v[34:37], v[194:197], v[184:187], v[34:37]
	v_mfma_f32_16x16x32_bf16 v[18:21], v[202:205], v[184:187], v[18:21]
	v_mfma_f32_16x16x32_bf16 v[50:53], v[198:201], v[150:153], v[50:53]
	v_mfma_f32_16x16x32_bf16 v[26:29], v[206:209], v[150:153], v[26:29]
	v_mfma_f32_16x16x32_bf16 v[46:49], v[198:201], v[172:175], v[46:49]
	v_mfma_f32_16x16x32_bf16 v[30:33], v[206:209], v[172:175], v[30:33]
	v_mfma_f32_16x16x32_bf16 v[38:41], v[198:201], v[180:183], v[38:41]
	v_mfma_f32_16x16x32_bf16 v[22:25], v[206:209], v[180:183], v[22:25]
	v_mfma_f32_16x16x32_bf16 v[34:37], v[198:201], v[190:193], v[34:37]
	v_mfma_f32_16x16x32_bf16 v[18:21], v[206:209], v[190:193], v[18:21]
	s_add_i32 s45, s45, 2
	s_add_u32 s28, s28, 0x100
	s_addc_u32 s29, s29, 0
	s_mov_b64 s[6:7], s[88:89]
	s_add_u32 s88, s6, 0x100
	s_addc_u32 s89, s7, 0
	s_cmp_eq_u32 s45, 12
	s_cselect_b32 s93, s17, s89
	s_cselect_b32 s92, s22, s88
	s_cselect_b32 s91, s15, s29
	s_cselect_b32 s90, s23, s28
	s_cmp_gt_u32 s45, 13
	s_barrier
	s_cbranch_scc0 .LBB0_919
	s_waitcnt lgkmcnt(0)
	v_mov_b32_e32 v131, v252
	s_lshl_b32 s88, s5, 7
	v_bfe_u32 v130, v131, 4, 2
	v_and_b32_e32 v134, 15, v131
	v_lshlrev_b32_e32 v0, 4, v130
	s_ashr_i32 s89, s88, 31
	s_lshl_b32 s15, s4, 8
	v_or3_b32 v135, v0, s97, v134
	s_lshl_b64 s[4:5], s[88:89], 2
	v_lshrrev_b32_e32 v140, 1, v135
	s_add_u32 s4, s73, s4
	s_addc_u32 s5, s74, s5
	v_lshlrev_b32_e32 v0, 2, v140
	v_and_b32_e32 v144, 1, v131
	v_lshl_add_u64 v[132:133], s[4:5], 0, v[0:1]
	v_cmp_eq_u32_e32 vcc, 1, v144
	v_mov_b32_e32 v0, 0xb00
	s_movk_i32 s4, 0x5000
	v_cndmask_b32_e32 v141, 0, v0, vcc
	v_lshlrev_b32_e32 v0, 2, v141
	v_lshl_add_u64 v[132:133], v[132:133], 0, v[0:1]
	v_add_co_u32_e32 v138, vcc, s4, v132
	s_mov_b32 s4, 0xb000
	s_nop 0
	v_addc_co_u32_e32 v139, vcc, 0, v133, vcc
	global_load_dword v136, v[132:133], off
	global_load_dword v137, v[138:139], off offset:2048
	v_add_co_u32_e32 v132, vcc, s4, v132
	v_add_u32_e32 v0, s88, v141
	s_nop 0
	v_addc_co_u32_e32 v133, vcc, 0, v133, vcc
	global_load_dword v138, v[132:133], off
	v_or_b32_e32 v132, v140, v0
	v_ashrrev_i32_e32 v133, 31, v132
	v_lshl_add_u64 v[132:133], v[132:133], 2, s[12:13]
	global_load_dword v139, v[132:133], off
	v_lshl_add_u32 v152, v135, 4, s78
	v_and_b32_e32 v135, 63, v131
	v_cmp_eq_u32_e32 vcc, 0, v144
	v_or_b32_e32 v0, s97, v135
	v_lshrrev_b32_e32 v0, 1, v0
	v_and_or_b32 v131, v0, 63, s55
	v_add_u32_e32 v132, s15, v131
	v_ashrrev_i32_e32 v133, 31, v132
	v_lshlrev_b64 v[132:133], 6, v[132:133]
	v_lshl_add_u64 v[132:133], s[10:11], 0, v[132:133]
	v_lshlrev_b32_e32 v0, 5, v144
	v_lshl_add_u64 v[132:133], v[132:133], 0, v[0:1]
	global_load_dwordx4 v[148:151], v[132:133], off offset:16
	global_load_dwordx4 v[140:143], v[132:133], off
	s_waitcnt vmcnt(2)
	ds_write_b128 v152, v[136:139]
	s_waitcnt vmcnt(0)
	v_add_f32_e32 v133, v150, v151
	v_add_f32_e32 v0, v140, v141
	v_add_f32_e32 v132, v142, v143
	v_add_f32_e32 v0, v0, v132
	v_add_f32_e32 v132, v148, v149
	v_add_f32_e32 v132, v132, v133
	v_add_f32_e32 v0, v0, v132
	v_lshlrev_b32_e32 v132, 2, v135
	v_xor_b32_e32 v132, 4, v132
	ds_bpermute_b32 v132, v132, v0
	s_and_saveexec_b64 s[4:5], vcc
	s_cbranch_execz .LBB0_922
	s_waitcnt lgkmcnt(0)
	v_add_f32_e32 v0, v0, v132
	v_mov_b32_e32 v132, 0x358637bd
	v_fmamk_f32 v0, v0, 0x3a800000, v132
	s_mov_b32 s6, 0x800000
	v_mul_f32_e32 v132, 0x4b800000, v0
	v_cmp_gt_f32_e32 vcc, s6, v0
	v_lshl_add_u32 v131, v131, 2, 0
	v_add_u32_e32 v131, 0x20000, v131
	v_cndmask_b32_e32 v0, v0, v132, vcc
	v_rsq_f32_e32 v0, v0
	s_nop 0
	v_mul_f32_e32 v132, 0x45800000, v0
	v_cndmask_b32_e32 v0, v0, v132, vcc
	ds_write_b32 v131, v0

.LBB0_1090:
	v_lshl_add_u64 v[178:179], s[16:17], 0, v[196:197]
	s_add_i32 m0, s39, 0xc000
	ds_read_b128 v[146:149], v213
	ds_read_b128 v[150:153], v213 offset:1024
	ds_read_b128 v[154:157], v213 offset:2048
	ds_read_b128 v[158:161], v213 offset:3072
	ds_read_b128 v[162:165], v213 offset:4096
	ds_read_b128 v[166:169], v213 offset:5120
	ds_read_b128 v[170:173], v213 offset:6144
	ds_read_b128 v[174:177], v213 offset:7168
	global_load_lds_dwordx4 v[178:179], off
	s_add_i32 m0, s39, 0xe000
	v_lshl_add_u64 v[178:179], s[16:17], 0, v[198:199]
	global_load_lds_dwordx4 v[178:179], off
	s_waitcnt lgkmcnt(8)
	s_barrier
	s_waitcnt lgkmcnt(0)
	v_mfma_f32_16x16x32_bf16 v[126:129], v[130:133], v[146:149], v[126:129]
	v_mfma_f32_16x16x32_bf16 v[122:125], v[138:141], v[146:149], v[122:125]
	v_mfma_f32_16x16x32_bf16 v[110:113], v[130:133], v[154:157], v[110:113]
	v_mfma_f32_16x16x32_bf16 v[106:109], v[138:141], v[154:157], v[106:109]
	v_mfma_f32_16x16x32_bf16 v[94:97], v[130:133], v[162:165], v[94:97]
	v_mfma_f32_16x16x32_bf16 v[90:93], v[138:141], v[162:165], v[90:93]
	v_mfma_f32_16x16x32_bf16 v[78:81], v[130:133], v[170:173], v[78:81]
	v_mfma_f32_16x16x32_bf16 v[74:77], v[138:141], v[170:173], v[74:77]
	v_mfma_f32_16x16x32_bf16 v[126:129], v[134:137], v[150:153], v[126:129]
	v_mfma_f32_16x16x32_bf16 v[122:125], v[142:145], v[150:153], v[122:125]
	v_mfma_f32_16x16x32_bf16 v[110:113], v[134:137], v[158:161], v[110:113]
	v_mfma_f32_16x16x32_bf16 v[106:109], v[142:145], v[158:161], v[106:109]
	v_mfma_f32_16x16x32_bf16 v[94:97], v[134:137], v[166:169], v[94:97]
	v_mfma_f32_16x16x32_bf16 v[90:93], v[142:145], v[166:169], v[90:93]
	v_mfma_f32_16x16x32_bf16 v[78:81], v[134:137], v[174:177], v[78:81]
	v_mfma_f32_16x16x32_bf16 v[74:77], v[142:145], v[174:177], v[74:77]
	s_barrier
	s_add_i32 s91, 0, 0x14000
	v_add_u32_e32 v186, s91, v212
	s_add_i32 s16, s90, s38
	ds_read_b128 v[178:181], v186
	ds_read_b128 v[182:185], v186 offset:1024
	ds_read_b128 v[200:203], v186 offset:2048
	ds_read_b128 v[204:207], v186 offset:3072
	s_mov_b32 m0, s16
	global_load_lds_dwordx4 v0, s[86:87]
	s_add_i32 m0, s16, 0x2000
	s_nop 0
	global_load_lds_dwordx4 v194, s[86:87]
	s_barrier
	s_waitcnt lgkmcnt(0)
	v_mfma_f32_16x16x32_bf16 v[118:121], v[178:181], v[146:149], v[118:121]
	v_mfma_f32_16x16x32_bf16 v[114:117], v[200:203], v[146:149], v[114:117]
	v_mfma_f32_16x16x32_bf16 v[102:105], v[178:181], v[154:157], v[102:105]
	v_mfma_f32_16x16x32_bf16 v[98:101], v[200:203], v[154:157], v[98:101]
	v_mfma_f32_16x16x32_bf16 v[86:89], v[178:181], v[162:165], v[86:89]
	v_mfma_f32_16x16x32_bf16 v[82:85], v[200:203], v[162:165], v[82:85]
	v_mfma_f32_16x16x32_bf16 v[70:73], v[178:181], v[170:173], v[70:73]
	v_mfma_f32_16x16x32_bf16 v[66:69], v[200:203], v[170:173], v[66:69]
	v_mfma_f32_16x16x32_bf16 v[118:121], v[182:185], v[150:153], v[118:121]
	v_mfma_f32_16x16x32_bf16 v[114:117], v[204:207], v[150:153], v[114:117]
	v_mfma_f32_16x16x32_bf16 v[102:105], v[182:185], v[158:161], v[102:105]
	v_mfma_f32_16x16x32_bf16 v[98:101], v[204:207], v[158:161], v[98:101]
	v_mfma_f32_16x16x32_bf16 v[86:89], v[182:185], v[166:169], v[86:89]
	v_mfma_f32_16x16x32_bf16 v[82:85], v[204:207], v[166:169], v[82:85]
	v_mfma_f32_16x16x32_bf16 v[70:73], v[182:185], v[174:177], v[70:73]
	v_mfma_f32_16x16x32_bf16 v[66:69], v[204:207], v[174:177], v[66:69]
	s_mov_b32 m0, s39
	v_lshl_add_u64 v[210:211], s[88:89], 0, v[190:191]
	s_barrier
	ds_read_b128 v[146:149], v213 offset:16384
	ds_read_b128 v[150:153], v213 offset:17408
	ds_read_b128 v[154:157], v213 offset:18432
	ds_read_b128 v[158:161], v213 offset:19456
	ds_read_b128 v[162:165], v213 offset:20480
	ds_read_b128 v[166:169], v213 offset:21504
	ds_read_b128 v[170:173], v213 offset:22528
	ds_read_b128 v[174:177], v213 offset:23552
	global_load_lds_dwordx4 v[210:211], off
	s_mov_b32 m0, s42
	v_lshl_add_u64 v[214:215], s[88:89], 0, v[192:193]
	global_load_lds_dwordx4 v[214:215], off
	s_waitcnt vmcnt(10)
	s_barrier
	s_waitcnt lgkmcnt(0)
	v_mfma_f32_16x16x32_bf16 v[62:65], v[130:133], v[146:149], v[62:65]
	v_mfma_f32_16x16x32_bf16 v[58:61], v[138:141], v[146:149], v[58:61]
	v_mfma_f32_16x16x32_bf16 v[46:49], v[130:133], v[154:157], v[46:49]
	v_mfma_f32_16x16x32_bf16 v[42:45], v[138:141], v[154:157], v[42:45]
	v_mfma_f32_16x16x32_bf16 v[30:33], v[130:133], v[162:165], v[30:33]
	v_mfma_f32_16x16x32_bf16 v[26:29], v[138:141], v[162:165], v[26:29]
	v_mfma_f32_16x16x32_bf16 v[14:17], v[130:133], v[170:173], v[14:17]
	v_mfma_f32_16x16x32_bf16 v[10:13], v[138:141], v[170:173], v[10:13]
	v_mfma_f32_16x16x32_bf16 v[62:65], v[134:137], v[150:153], v[62:65]
	v_mfma_f32_16x16x32_bf16 v[58:61], v[142:145], v[150:153], v[58:61]
	v_mfma_f32_16x16x32_bf16 v[46:49], v[134:137], v[158:161], v[46:49]
	v_mfma_f32_16x16x32_bf16 v[42:45], v[142:145], v[158:161], v[42:45]
	v_mfma_f32_16x16x32_bf16 v[30:33], v[134:137], v[166:169], v[30:33]
	v_mfma_f32_16x16x32_bf16 v[26:29], v[142:145], v[166:169], v[26:29]
	v_mfma_f32_16x16x32_bf16 v[14:17], v[134:137], v[174:177], v[14:17]
	v_mfma_f32_16x16x32_bf16 v[10:13], v[142:145], v[174:177], v[10:13]
	s_barrier
	s_add_u32 s16, s86, 0xb0000
	s_addc_u32 s17, s87, 0
	s_add_i32 s90, s91, s38
	s_mov_b32 m0, s90
	s_nop 0
	global_load_lds_dwordx4 v0, s[16:17]
	s_add_i32 m0, s90, 0x2000
	s_nop 0
	global_load_lds_dwordx4 v194, s[16:17]
	s_add_i32 s90, 0, 0x18000
	v_add_u32_e32 v142, s90, v212
	ds_read_b128 v[130:133], v142
	ds_read_b128 v[134:137], v142 offset:1024
	ds_read_b128 v[138:141], v142 offset:2048
	ds_read_b128 v[142:145], v142 offset:3072
	s_waitcnt vmcnt(6)
	s_barrier
	v_mfma_f32_16x16x32_bf16 v[54:57], v[178:181], v[146:149], v[54:57]
	v_mfma_f32_16x16x32_bf16 v[50:53], v[200:203], v[146:149], v[50:53]
	v_mfma_f32_16x16x32_bf16 v[38:41], v[178:181], v[154:157], v[38:41]
	v_mfma_f32_16x16x32_bf16 v[34:37], v[200:203], v[154:157], v[34:37]
	v_mfma_f32_16x16x32_bf16 v[22:25], v[178:181], v[162:165], v[22:25]
	v_mfma_f32_16x16x32_bf16 v[18:21], v[200:203], v[162:165], v[18:21]
	v_mfma_f32_16x16x32_bf16 v[6:9], v[178:181], v[170:173], v[6:9]
	v_mfma_f32_16x16x32_bf16 v[2:5], v[200:203], v[170:173], v[2:5]
	v_mfma_f32_16x16x32_bf16 v[54:57], v[182:185], v[150:153], v[54:57]
	v_mfma_f32_16x16x32_bf16 v[50:53], v[204:207], v[150:153], v[50:53]
	v_mfma_f32_16x16x32_bf16 v[38:41], v[182:185], v[158:161], v[38:41]
	v_mfma_f32_16x16x32_bf16 v[34:37], v[204:207], v[158:161], v[34:37]
	v_mfma_f32_16x16x32_bf16 v[22:25], v[182:185], v[166:169], v[22:25]
	v_mfma_f32_16x16x32_bf16 v[18:21], v[204:207], v[166:169], v[18:21]
	v_mfma_f32_16x16x32_bf16 v[6:9], v[182:185], v[174:177], v[6:9]
	v_mfma_f32_16x16x32_bf16 v[2:5], v[204:207], v[174:177], v[2:5]
	s_barrier
	s_add_u32 s16, s88, 0xb0000
	s_addc_u32 s17, s89, 0
	s_mov_b32 m0, s43
	ds_read_b128 v[146:149], v213 offset:32768
	ds_read_b128 v[150:153], v213 offset:33792
	ds_read_b128 v[154:157], v213 offset:34816
	ds_read_b128 v[158:161], v213 offset:35840
	ds_read_b128 v[162:165], v213 offset:36864
	ds_read_b128 v[166:169], v213 offset:37888
	ds_read_b128 v[170:173], v213 offset:38912
	ds_read_b128 v[174:177], v213 offset:39936
	global_load_lds_dwordx4 v190, s[16:17]
	s_mov_b32 m0, s44
	s_nop 0
	global_load_lds_dwordx4 v192, s[16:17]
	s_waitcnt lgkmcnt(8)
	s_barrier
	s_waitcnt lgkmcnt(0)
	v_mfma_f32_16x16x32_bf16 v[126:129], v[130:133], v[146:149], v[126:129]
	v_mfma_f32_16x16x32_bf16 v[122:125], v[138:141], v[146:149], v[122:125]
	v_mfma_f32_16x16x32_bf16 v[110:113], v[130:133], v[154:157], v[110:113]
	v_mfma_f32_16x16x32_bf16 v[106:109], v[138:141], v[154:157], v[106:109]
	v_mfma_f32_16x16x32_bf16 v[94:97], v[130:133], v[162:165], v[94:97]
	v_mfma_f32_16x16x32_bf16 v[90:93], v[138:141], v[162:165], v[90:93]
	v_mfma_f32_16x16x32_bf16 v[78:81], v[130:133], v[170:173], v[78:81]
	v_mfma_f32_16x16x32_bf16 v[74:77], v[138:141], v[170:173], v[74:77]
	v_mfma_f32_16x16x32_bf16 v[126:129], v[134:137], v[150:153], v[126:129]
	v_mfma_f32_16x16x32_bf16 v[122:125], v[142:145], v[150:153], v[122:125]
	v_mfma_f32_16x16x32_bf16 v[110:113], v[134:137], v[158:161], v[110:113]
	v_mfma_f32_16x16x32_bf16 v[106:109], v[142:145], v[158:161], v[106:109]
	v_mfma_f32_16x16x32_bf16 v[94:97], v[134:137], v[166:169], v[94:97]
	v_mfma_f32_16x16x32_bf16 v[90:93], v[142:145], v[166:169], v[90:93]
	v_mfma_f32_16x16x32_bf16 v[78:81], v[134:137], v[174:177], v[78:81]
	v_mfma_f32_16x16x32_bf16 v[74:77], v[142:145], v[174:177], v[74:77]
	s_barrier
	s_add_i32 s88, 0, 0x1c000
	s_add_i32 s16, s90, s38
	v_add_u32_e32 v204, s88, v212
	s_mov_b32 m0, s16
	ds_read_b128 v[178:181], v204
	ds_read_b128 v[182:185], v204 offset:1024
	ds_read_b128 v[200:203], v204 offset:2048
	ds_read_b128 v[204:207], v204 offset:3072
	s_add_u32 s98, s86, s40
	s_addc_u32 s99, s87, s41
	global_load_lds_dwordx4 v0, s[98:99]
	s_add_i32 m0, s16, 0x2000
	s_add_u32 s98, s86, s40
	s_addc_u32 s99, s87, s41
	global_load_lds_dwordx4 v194, s[98:99]
	s_barrier
	s_waitcnt lgkmcnt(0)
	v_mfma_f32_16x16x32_bf16 v[118:121], v[178:181], v[146:149], v[118:121]
	v_mfma_f32_16x16x32_bf16 v[114:117], v[200:203], v[146:149], v[114:117]
	v_mfma_f32_16x16x32_bf16 v[102:105], v[178:181], v[154:157], v[102:105]
	v_mfma_f32_16x16x32_bf16 v[98:101], v[200:203], v[154:157], v[98:101]
	v_mfma_f32_16x16x32_bf16 v[86:89], v[178:181], v[162:165], v[86:89]
	v_mfma_f32_16x16x32_bf16 v[82:85], v[200:203], v[162:165], v[82:85]
	v_mfma_f32_16x16x32_bf16 v[70:73], v[178:181], v[170:173], v[70:73]
	v_mfma_f32_16x16x32_bf16 v[66:69], v[200:203], v[170:173], v[66:69]
	v_mfma_f32_16x16x32_bf16 v[118:121], v[182:185], v[150:153], v[118:121]
	v_mfma_f32_16x16x32_bf16 v[114:117], v[204:207], v[150:153], v[114:117]
	v_mfma_f32_16x16x32_bf16 v[102:105], v[182:185], v[158:161], v[102:105]
	v_mfma_f32_16x16x32_bf16 v[98:101], v[204:207], v[158:161], v[98:101]
	v_mfma_f32_16x16x32_bf16 v[86:89], v[182:185], v[166:169], v[86:89]
	v_mfma_f32_16x16x32_bf16 v[82:85], v[204:207], v[166:169], v[82:85]
	v_mfma_f32_16x16x32_bf16 v[70:73], v[182:185], v[174:177], v[70:73]
	v_mfma_f32_16x16x32_bf16 v[66:69], v[204:207], v[174:177], v[66:69]
	s_mov_b32 m0, s60
	v_lshl_add_u64 v[186:187], v[210:211], 0, s[40:41]
	s_barrier
	ds_read_b128 v[146:149], v213 offset:49152
	ds_read_b128 v[150:153], v213 offset:50176
	ds_read_b128 v[154:157], v213 offset:51200
	ds_read_b128 v[158:161], v213 offset:52224
	ds_read_b128 v[162:165], v213 offset:53248
	ds_read_b128 v[166:169], v213 offset:54272
	ds_read_b128 v[170:173], v213 offset:55296
	ds_read_b128 v[174:177], v213 offset:56320
	global_load_lds_dwordx4 v[186:187], off
	s_mov_b32 m0, s61
	v_lshl_add_u64 v[186:187], v[214:215], 0, s[40:41]
	global_load_lds_dwordx4 v[186:187], off
	s_waitcnt vmcnt(10)
	s_barrier
	s_waitcnt lgkmcnt(0)
	v_mfma_f32_16x16x32_bf16 v[62:65], v[130:133], v[146:149], v[62:65]
	v_mfma_f32_16x16x32_bf16 v[58:61], v[138:141], v[146:149], v[58:61]
	v_mfma_f32_16x16x32_bf16 v[46:49], v[130:133], v[154:157], v[46:49]
	v_mfma_f32_16x16x32_bf16 v[42:45], v[138:141], v[154:157], v[42:45]
	v_mfma_f32_16x16x32_bf16 v[30:33], v[130:133], v[162:165], v[30:33]
	v_mfma_f32_16x16x32_bf16 v[26:29], v[138:141], v[162:165], v[26:29]
	v_mfma_f32_16x16x32_bf16 v[14:17], v[130:133], v[170:173], v[14:17]
	v_mfma_f32_16x16x32_bf16 v[10:13], v[138:141], v[170:173], v[10:13]
	v_mfma_f32_16x16x32_bf16 v[62:65], v[134:137], v[150:153], v[62:65]
	v_mfma_f32_16x16x32_bf16 v[58:61], v[142:145], v[150:153], v[58:61]
	v_mfma_f32_16x16x32_bf16 v[46:49], v[134:137], v[158:161], v[46:49]
	v_mfma_f32_16x16x32_bf16 v[42:45], v[142:145], v[158:161], v[42:45]
	v_mfma_f32_16x16x32_bf16 v[30:33], v[134:137], v[166:169], v[30:33]
	v_mfma_f32_16x16x32_bf16 v[26:29], v[142:145], v[166:169], v[26:29]
	v_mfma_f32_16x16x32_bf16 v[14:17], v[134:137], v[174:177], v[14:17]
	v_mfma_f32_16x16x32_bf16 v[10:13], v[142:145], v[174:177], v[10:13]
	s_barrier
	s_add_u32 s16, s86, 0xb0080
	s_addc_u32 s17, s87, 0
	s_add_i32 s86, s88, s38
	s_mov_b32 m0, s86
	s_nop 0
	global_load_lds_dwordx4 v0, s[16:17]
	s_add_i32 m0, s86, 0x2000
	s_nop 0
	global_load_lds_dwordx4 v194, s[16:17]
	s_add_i32 s90, 0, 0x10000
	v_add_u32_e32 v142, s90, v212
	ds_read_b128 v[130:133], v142
	ds_read_b128 v[134:137], v142 offset:1024
	ds_read_b128 v[138:141], v142 offset:2048
	ds_read_b128 v[142:145], v142 offset:3072
	s_waitcnt vmcnt(6)
	s_barrier
	v_mfma_f32_16x16x32_bf16 v[54:57], v[178:181], v[146:149], v[54:57]
	v_mfma_f32_16x16x32_bf16 v[50:53], v[200:203], v[146:149], v[50:53]
	v_mfma_f32_16x16x32_bf16 v[38:41], v[178:181], v[154:157], v[38:41]
	v_mfma_f32_16x16x32_bf16 v[34:37], v[200:203], v[154:157], v[34:37]
	v_mfma_f32_16x16x32_bf16 v[22:25], v[178:181], v[162:165], v[22:25]
	v_mfma_f32_16x16x32_bf16 v[18:21], v[200:203], v[162:165], v[18:21]
	v_mfma_f32_16x16x32_bf16 v[6:9], v[178:181], v[170:173], v[6:9]
	v_mfma_f32_16x16x32_bf16 v[2:5], v[200:203], v[170:173], v[2:5]
	v_mfma_f32_16x16x32_bf16 v[54:57], v[182:185], v[150:153], v[54:57]
	v_mfma_f32_16x16x32_bf16 v[50:53], v[204:207], v[150:153], v[50:53]
	v_mfma_f32_16x16x32_bf16 v[38:41], v[182:185], v[158:161], v[38:41]
	v_mfma_f32_16x16x32_bf16 v[34:37], v[204:207], v[158:161], v[34:37]
	v_mfma_f32_16x16x32_bf16 v[22:25], v[182:185], v[166:169], v[22:25]
	v_mfma_f32_16x16x32_bf16 v[18:21], v[204:207], v[166:169], v[18:21]
	v_mfma_f32_16x16x32_bf16 v[6:9], v[182:185], v[174:177], v[6:9]
	v_mfma_f32_16x16x32_bf16 v[2:5], v[204:207], v[174:177], v[2:5]
	s_add_i32 s79, s79, 2
	s_add_u32 s34, s34, 0x100
	s_addc_u32 s78, s78, 0
	s_mov_b64 s[16:17], s[84:85]
	s_add_u32 s84, s16, 0x100
	s_addc_u32 s85, s17, 0
	s_cmp_eq_u32 s79, 40
	s_cselect_b32 s89, s5, s85
	s_cselect_b32 s88, s4, s84
	s_cselect_b32 s87, s7, s78
	s_cselect_b32 s86, s6, s34
	s_cmp_gt_u32 s79, 41
	s_barrier
	s_cbranch_scc0 .LBB0_1090
	s_waitcnt lgkmcnt(0)
	s_lshl_b32 s16, s23, 8
	v_mov_b32_e32 v186, v252
	s_add_i32 s16, s16, s47
	s_nop 0
	v_and_or_b32 v202, v186, 15, s16
	s_lshl_b32 s16, s22, 8
	s_or_b32 s16, s16, s55
	v_lshrrev_b32_e32 v130, 1, v186
	v_and_or_b32 v200, v130, 24, s16
	v_ashrrev_i32_e32 v201, 31, v200
	v_ashrrev_i32_e32 v203, 31, v202
	v_lshl_add_u64 v[204:205], v[200:201], 2, s[12:13]
	v_lshlrev_b64 v[130:131], 12, v[202:203]
	v_lshl_add_u64 v[130:131], v[204:205], 0, v[130:131]
	global_load_dwordx4 v[216:219], v[130:131], off offset:16
	global_load_dwordx4 v[220:223], v[130:131], off
	global_load_dwordx4 v[178:181], v[130:131], off offset:528
	global_load_dwordx4 v[182:185], v[130:131], off offset:512
	v_or_b32_e32 v210, 16, v202
	v_ashrrev_i32_e32 v211, 31, v210
	v_lshlrev_b64 v[130:131], 12, v[210:211]
	v_or_b32_e32 v208, 32, v202
	v_lshl_add_u64 v[130:131], v[204:205], 0, v[130:131]
	v_ashrrev_i32_e32 v209, 31, v208
	global_load_dwordx4 v[170:173], v[130:131], off offset:16
	global_load_dwordx4 v[174:177], v[130:131], off
	global_load_dwordx4 v[162:165], v[130:131], off offset:528
	global_load_dwordx4 v[166:169], v[130:131], off offset:512
	v_lshlrev_b64 v[130:131], 12, v[208:209]
	v_or_b32_e32 v206, 48, v202
	v_lshl_add_u64 v[130:131], v[204:205], 0, v[130:131]
	v_ashrrev_i32_e32 v207, 31, v206
	global_load_dwordx4 v[154:157], v[130:131], off offset:16
	global_load_dwordx4 v[158:161], v[130:131], off
	global_load_dwordx4 v[138:141], v[130:131], off offset:528
	global_load_dwordx4 v[142:145], v[130:131], off offset:512
	v_lshlrev_b64 v[130:131], 12, v[206:207]
	v_lshl_add_u64 v[134:135], v[204:205], 0, v[130:131]
	global_load_dwordx4 v[146:149], v[134:135], off offset:16
	global_load_dwordx4 v[150:153], v[134:135], off
	global_load_dwordx4 v[130:133], v[134:135], off offset:528
	s_nop 0
	global_load_dwordx4 v[134:137], v[134:135], off offset:512
	v_and_b32_e32 v186, 63, v186
	v_lshlrev_b32_e32 v187, 2, v186
	v_xor_b32_e32 v215, 64, v187
	v_xor_b32_e32 v214, 0x80, v187
	v_cmp_gt_u32_e32 vcc, 16, v186
	v_lshlrev_b64 v[186:187], 10, v[202:203]
	v_lshl_add_u64 v[186:187], v[186:187], 0, v[200:201]
	s_lshl_b32 s16, s22, 2
	s_ashr_i32 s17, s16, 31
	s_waitcnt vmcnt(0)
	v_pk_add_f32 v[124:125], v[124:125], v[218:219]
	v_pk_add_f32 v[128:129], v[128:129], v[222:223]
	v_pk_add_f32 v[126:127], v[126:127], v[220:221]
	v_pk_mul_f32 v[218:219], v[128:129], v[128:129]
	v_pk_mul_f32 v[220:221], v[126:127], v[126:127]
	v_pk_add_f32 v[122:123], v[122:123], v[216:217]
	v_lshl_add_u64 v[216:217], v[186:187], 2, s[14:15]
	v_add_f32_e32 v220, v220, v221
	v_add_f32_e32 v218, v218, v219
	global_store_dwordx4 v[216:217], v[126:129], off
	global_store_dwordx4 v[216:217], v[122:125], off offset:16
	v_add_f32_e32 v222, v220, v218
	v_pk_mul_f32 v[220:221], v[122:123], v[122:123]
	v_cvt_pk_bf16_f32 v126, v126, v127
	v_cvt_pk_bf16_f32 v127, v128, v129
	v_cvt_pk_bf16_f32 v128, v122, v123
	v_cvt_pk_bf16_f32 v129, v124, v125
	v_lshl_add_u64 v[122:123], v[186:187], 1, s[80:81]
	v_pk_add_f32 v[120:121], v[120:121], v[184:185]
	v_pk_add_f32 v[118:119], v[118:119], v[182:183]
	v_pk_mul_f32 v[218:219], v[124:125], v[124:125]
	global_store_dwordx4 v[122:123], v[126:129], off
	v_pk_mul_f32 v[124:125], v[120:121], v[120:121]
	v_pk_add_f32 v[116:117], v[116:117], v[180:181]
	v_pk_mul_f32 v[126:127], v[118:119], v[118:119]
	v_pk_add_f32 v[114:115], v[114:115], v[178:179]
	v_add_f32_e32 v126, v126, v127
	v_add_f32_e32 v124, v124, v125
	v_add_f32_e32 v128, v126, v124
	v_pk_mul_f32 v[124:125], v[116:117], v[116:117]
	v_pk_mul_f32 v[126:127], v[114:115], v[114:115]
	v_add_f32_e32 v220, v220, v221
	v_add_f32_e32 v218, v218, v219
	v_add_f32_e32 v126, v126, v127
	v_add_f32_e32 v124, v124, v125
	v_add_f32_e32 v218, v220, v218
	v_add_f32_e32 v124, v126, v124
	v_add_f32_e32 v218, v222, v218
	v_add_f32_e32 v124, v128, v124
	v_add_f32_e32 v124, v218, v124
	global_store_dwordx4 v[216:217], v[118:121], off offset:512
	global_store_dwordx4 v[216:217], v[114:117], off offset:528
	s_nop 0
	v_cvt_pk_bf16_f32 v118, v118, v119
	v_cvt_pk_bf16_f32 v119, v120, v121
	v_cvt_pk_bf16_f32 v120, v114, v115
	ds_bpermute_b32 v114, v215, v124
	v_cvt_pk_bf16_f32 v121, v116, v117
	global_store_dwordx4 v[122:123], v[118:121], off offset:256
	s_waitcnt lgkmcnt(0)
	v_add_f32_e32 v114, v124, v114
	ds_bpermute_b32 v115, v214, v114
	s_and_saveexec_b64 s[22:23], vcc
	s_cbranch_execz .LBB0_1093
	v_lshlrev_b64 v[116:117], 6, v[202:203]
	v_lshl_add_u64 v[116:117], s[82:83], 0, v[116:117]
	v_lshl_add_u64 v[116:117], s[16:17], 2, v[116:117]
	s_lshl_b32 s34, s45, 2
	v_lshl_add_u64 v[116:117], v[116:117], 0, s[34:35]
	s_waitcnt lgkmcnt(0)
	v_add_f32_e32 v114, v114, v115
	global_store_dword v[116:117], v114, off

.LBB0_1209:
	s_waitcnt lgkmcnt(0)
	s_add_i32 m0, s39, 0xc000
	ds_read_b128 v[158:161], v171
	ds_read_b128 v[162:165], v171 offset:1024
	ds_read_b128 v[166:169], v171 offset:2048
	ds_read_b128 v[172:175], v171 offset:3072
	ds_read_b128 v[176:179], v171 offset:4096
	ds_read_b128 v[180:183], v171 offset:5120
	ds_read_b128 v[184:187], v171 offset:6144
	ds_read_b128 v[190:193], v171 offset:7168
	global_load_lds_dwordx4 v154, s[88:89]
	s_add_i32 m0, s39, 0xe000
	s_nop 0
	global_load_lds_dwordx4 v156, s[88:89]
	s_waitcnt lgkmcnt(8)
	s_barrier
	s_waitcnt lgkmcnt(0)
	v_mfma_f32_16x16x32_bf16 v[126:129], v[130:133], v[158:161], v[126:129]
	v_mfma_f32_16x16x32_bf16 v[122:125], v[138:141], v[158:161], v[122:125]
	v_mfma_f32_16x16x32_bf16 v[110:113], v[130:133], v[166:169], v[110:113]
	v_mfma_f32_16x16x32_bf16 v[106:109], v[138:141], v[166:169], v[106:109]
	v_mfma_f32_16x16x32_bf16 v[94:97], v[130:133], v[176:179], v[94:97]
	v_mfma_f32_16x16x32_bf16 v[90:93], v[138:141], v[176:179], v[90:93]
	v_mfma_f32_16x16x32_bf16 v[78:81], v[130:133], v[184:187], v[78:81]
	v_mfma_f32_16x16x32_bf16 v[74:77], v[138:141], v[184:187], v[74:77]
	v_mfma_f32_16x16x32_bf16 v[126:129], v[134:137], v[162:165], v[126:129]
	v_mfma_f32_16x16x32_bf16 v[122:125], v[142:145], v[162:165], v[122:125]
	v_mfma_f32_16x16x32_bf16 v[110:113], v[134:137], v[172:175], v[110:113]
	v_mfma_f32_16x16x32_bf16 v[106:109], v[142:145], v[172:175], v[106:109]
	v_mfma_f32_16x16x32_bf16 v[94:97], v[134:137], v[180:183], v[94:97]
	v_mfma_f32_16x16x32_bf16 v[90:93], v[142:145], v[180:183], v[90:93]
	v_mfma_f32_16x16x32_bf16 v[78:81], v[134:137], v[190:193], v[78:81]
	v_mfma_f32_16x16x32_bf16 v[74:77], v[142:145], v[190:193], v[74:77]
	s_barrier
	s_add_i32 s87, 0, 0x14000
	s_add_i32 s94, s94, s38
	v_add_u32_e32 v0, s87, v170
	s_mov_b32 m0, s94
	ds_read_b128 v[194:197], v0
	ds_read_b128 v[198:201], v0 offset:1024
	ds_read_b128 v[202:205], v0 offset:2048
	ds_read_b128 v[206:209], v0 offset:3072
	global_load_lds_dwordx4 v148, s[90:91]
	s_add_i32 m0, s94, 0x2000
	s_nop 0
	global_load_lds_dwordx4 v152, s[90:91]
	s_barrier
	s_waitcnt lgkmcnt(0)
	v_mfma_f32_16x16x32_bf16 v[118:121], v[194:197], v[158:161], v[118:121]
	v_mfma_f32_16x16x32_bf16 v[114:117], v[202:205], v[158:161], v[114:117]
	v_mfma_f32_16x16x32_bf16 v[102:105], v[194:197], v[166:169], v[102:105]
	v_mfma_f32_16x16x32_bf16 v[98:101], v[202:205], v[166:169], v[98:101]
	v_mfma_f32_16x16x32_bf16 v[86:89], v[194:197], v[176:179], v[86:89]
	v_mfma_f32_16x16x32_bf16 v[82:85], v[202:205], v[176:179], v[82:85]
	v_mfma_f32_16x16x32_bf16 v[70:73], v[194:197], v[184:187], v[70:73]
	v_mfma_f32_16x16x32_bf16 v[66:69], v[202:205], v[184:187], v[66:69]
	v_mfma_f32_16x16x32_bf16 v[118:121], v[198:201], v[162:165], v[118:121]
	v_mfma_f32_16x16x32_bf16 v[114:117], v[206:209], v[162:165], v[114:117]
	v_mfma_f32_16x16x32_bf16 v[102:105], v[198:201], v[172:175], v[102:105]
	v_mfma_f32_16x16x32_bf16 v[98:101], v[206:209], v[172:175], v[98:101]
	v_mfma_f32_16x16x32_bf16 v[86:89], v[198:201], v[180:183], v[86:89]
	v_mfma_f32_16x16x32_bf16 v[82:85], v[206:209], v[180:183], v[82:85]
	v_mfma_f32_16x16x32_bf16 v[70:73], v[198:201], v[190:193], v[70:73]
	v_mfma_f32_16x16x32_bf16 v[66:69], v[206:209], v[190:193], v[66:69]
	s_mov_b32 m0, s39
	v_lshl_add_u64 v[214:215], s[92:93], 0, v[146:147]
	s_barrier
	ds_read_b128 v[158:161], v171 offset:16384
	ds_read_b128 v[162:165], v171 offset:17408
	ds_read_b128 v[166:169], v171 offset:18432
	ds_read_b128 v[172:175], v171 offset:19456
	ds_read_b128 v[176:179], v171 offset:20480
	ds_read_b128 v[180:183], v171 offset:21504
	ds_read_b128 v[184:187], v171 offset:22528
	ds_read_b128 v[190:193], v171 offset:23552
	global_load_lds_dwordx4 v[214:215], off
	s_mov_b32 m0, s42
	v_lshl_add_u64 v[216:217], s[92:93], 0, v[150:151]
	global_load_lds_dwordx4 v[216:217], off
	s_waitcnt vmcnt(10)
	s_barrier
	s_waitcnt lgkmcnt(0)
	v_mfma_f32_16x16x32_bf16 v[62:65], v[130:133], v[158:161], v[62:65]
	v_mfma_f32_16x16x32_bf16 v[58:61], v[138:141], v[158:161], v[58:61]
	v_mfma_f32_16x16x32_bf16 v[46:49], v[130:133], v[166:169], v[46:49]
	v_mfma_f32_16x16x32_bf16 v[42:45], v[138:141], v[166:169], v[42:45]
	v_mfma_f32_16x16x32_bf16 v[30:33], v[130:133], v[176:179], v[30:33]
	v_mfma_f32_16x16x32_bf16 v[26:29], v[138:141], v[176:179], v[26:29]
	v_mfma_f32_16x16x32_bf16 v[14:17], v[130:133], v[184:187], v[14:17]
	v_mfma_f32_16x16x32_bf16 v[10:13], v[138:141], v[184:187], v[10:13]
	v_mfma_f32_16x16x32_bf16 v[62:65], v[134:137], v[162:165], v[62:65]
	v_mfma_f32_16x16x32_bf16 v[58:61], v[142:145], v[162:165], v[58:61]
	v_mfma_f32_16x16x32_bf16 v[46:49], v[134:137], v[172:175], v[46:49]
	v_mfma_f32_16x16x32_bf16 v[42:45], v[142:145], v[172:175], v[42:45]
	v_mfma_f32_16x16x32_bf16 v[30:33], v[134:137], v[180:183], v[30:33]
	v_mfma_f32_16x16x32_bf16 v[26:29], v[142:145], v[180:183], v[26:29]
	v_mfma_f32_16x16x32_bf16 v[14:17], v[134:137], v[190:193], v[14:17]
	v_mfma_f32_16x16x32_bf16 v[10:13], v[142:145], v[190:193], v[10:13]
	s_barrier
	s_add_u32 s94, s90, 0x40000
	s_addc_u32 s95, s91, 0
	s_add_i32 s87, s87, s38
	s_mov_b32 m0, s87
	s_nop 0
	global_load_lds_dwordx4 v148, s[94:95]
	s_add_i32 m0, s87, 0x2000
	s_nop 0
	global_load_lds_dwordx4 v152, s[94:95]
	s_add_i32 s87, 0, 0x18000
	v_add_u32_e32 v0, s87, v170
	ds_read_b128 v[130:133], v0
	ds_read_b128 v[134:137], v0 offset:1024
	ds_read_b128 v[138:141], v0 offset:2048
	ds_read_b128 v[142:145], v0 offset:3072
	s_waitcnt vmcnt(6)
	s_barrier
	v_mfma_f32_16x16x32_bf16 v[54:57], v[194:197], v[158:161], v[54:57]
	v_mfma_f32_16x16x32_bf16 v[50:53], v[202:205], v[158:161], v[50:53]
	v_mfma_f32_16x16x32_bf16 v[38:41], v[194:197], v[166:169], v[38:41]
	v_mfma_f32_16x16x32_bf16 v[34:37], v[202:205], v[166:169], v[34:37]
	v_mfma_f32_16x16x32_bf16 v[22:25], v[194:197], v[176:179], v[22:25]
	v_mfma_f32_16x16x32_bf16 v[18:21], v[202:205], v[176:179], v[18:21]
	v_mfma_f32_16x16x32_bf16 v[6:9], v[194:197], v[184:187], v[6:9]
	v_mfma_f32_16x16x32_bf16 v[2:5], v[202:205], v[184:187], v[2:5]
	v_mfma_f32_16x16x32_bf16 v[54:57], v[198:201], v[162:165], v[54:57]
	v_mfma_f32_16x16x32_bf16 v[50:53], v[206:209], v[162:165], v[50:53]
	v_mfma_f32_16x16x32_bf16 v[38:41], v[198:201], v[172:175], v[38:41]
	v_mfma_f32_16x16x32_bf16 v[34:37], v[206:209], v[172:175], v[34:37]
	v_mfma_f32_16x16x32_bf16 v[22:25], v[198:201], v[180:183], v[22:25]
	v_mfma_f32_16x16x32_bf16 v[18:21], v[206:209], v[180:183], v[18:21]
	v_mfma_f32_16x16x32_bf16 v[6:9], v[198:201], v[190:193], v[6:9]
	v_mfma_f32_16x16x32_bf16 v[2:5], v[206:209], v[190:193], v[2:5]
	s_barrier
	s_add_u32 s92, s92, 0x40000
	s_addc_u32 s93, s93, 0
	s_mov_b32 m0, s43
	ds_read_b128 v[158:161], v171 offset:32768
	ds_read_b128 v[162:165], v171 offset:33792
	ds_read_b128 v[166:169], v171 offset:34816
	ds_read_b128 v[172:175], v171 offset:35840
	ds_read_b128 v[176:179], v171 offset:36864
	ds_read_b128 v[180:183], v171 offset:37888
	ds_read_b128 v[184:187], v171 offset:38912
	ds_read_b128 v[190:193], v171 offset:39936
	global_load_lds_dwordx4 v146, s[92:93]
	s_mov_b32 m0, s44
	s_nop 0
	global_load_lds_dwordx4 v150, s[92:93]
	s_waitcnt lgkmcnt(8)
	s_barrier
	s_waitcnt lgkmcnt(0)
	v_mfma_f32_16x16x32_bf16 v[126:129], v[130:133], v[158:161], v[126:129]
	v_mfma_f32_16x16x32_bf16 v[122:125], v[138:141], v[158:161], v[122:125]
	v_mfma_f32_16x16x32_bf16 v[110:113], v[130:133], v[166:169], v[110:113]
	v_mfma_f32_16x16x32_bf16 v[106:109], v[138:141], v[166:169], v[106:109]
	v_mfma_f32_16x16x32_bf16 v[94:97], v[130:133], v[176:179], v[94:97]
	v_mfma_f32_16x16x32_bf16 v[90:93], v[138:141], v[176:179], v[90:93]
	v_mfma_f32_16x16x32_bf16 v[78:81], v[130:133], v[184:187], v[78:81]
	v_mfma_f32_16x16x32_bf16 v[74:77], v[138:141], v[184:187], v[74:77]
	v_mfma_f32_16x16x32_bf16 v[126:129], v[134:137], v[162:165], v[126:129]
	v_mfma_f32_16x16x32_bf16 v[122:125], v[142:145], v[162:165], v[122:125]
	v_mfma_f32_16x16x32_bf16 v[110:113], v[134:137], v[172:175], v[110:113]
	v_mfma_f32_16x16x32_bf16 v[106:109], v[142:145], v[172:175], v[106:109]
	v_mfma_f32_16x16x32_bf16 v[94:97], v[134:137], v[180:183], v[94:97]
	v_mfma_f32_16x16x32_bf16 v[90:93], v[142:145], v[180:183], v[90:93]
	v_mfma_f32_16x16x32_bf16 v[78:81], v[134:137], v[190:193], v[78:81]
	v_mfma_f32_16x16x32_bf16 v[74:77], v[142:145], v[190:193], v[74:77]
	s_barrier
	s_add_i32 s92, 0, 0x1c000
	s_add_i32 s87, s87, s38
	v_add_u32_e32 v0, s92, v170
	s_mov_b32 m0, s87
	ds_read_b128 v[194:197], v0
	ds_read_b128 v[198:201], v0 offset:1024
	ds_read_b128 v[202:205], v0 offset:2048
	ds_read_b128 v[206:209], v0 offset:3072
	s_add_u32 s98, s90, s40
	s_addc_u32 s99, s91, s41
	global_load_lds_dwordx4 v148, s[98:99]
	s_add_i32 m0, s87, 0x2000
	s_add_u32 s98, s90, s40
	s_addc_u32 s99, s91, s41
	global_load_lds_dwordx4 v152, s[98:99]
	s_barrier
	s_waitcnt lgkmcnt(0)
	v_mfma_f32_16x16x32_bf16 v[118:121], v[194:197], v[158:161], v[118:121]
	v_mfma_f32_16x16x32_bf16 v[114:117], v[202:205], v[158:161], v[114:117]
	v_mfma_f32_16x16x32_bf16 v[102:105], v[194:197], v[166:169], v[102:105]
	v_mfma_f32_16x16x32_bf16 v[98:101], v[202:205], v[166:169], v[98:101]
	v_mfma_f32_16x16x32_bf16 v[86:89], v[194:197], v[176:179], v[86:89]
	v_mfma_f32_16x16x32_bf16 v[82:85], v[202:205], v[176:179], v[82:85]
	v_mfma_f32_16x16x32_bf16 v[70:73], v[194:197], v[184:187], v[70:73]
	v_mfma_f32_16x16x32_bf16 v[66:69], v[202:205], v[184:187], v[66:69]
	v_mfma_f32_16x16x32_bf16 v[118:121], v[198:201], v[162:165], v[118:121]
	v_mfma_f32_16x16x32_bf16 v[114:117], v[206:209], v[162:165], v[114:117]
	v_mfma_f32_16x16x32_bf16 v[102:105], v[198:201], v[172:175], v[102:105]
	v_mfma_f32_16x16x32_bf16 v[98:101], v[206:209], v[172:175], v[98:101]
	v_mfma_f32_16x16x32_bf16 v[86:89], v[198:201], v[180:183], v[86:89]
	v_mfma_f32_16x16x32_bf16 v[82:85], v[206:209], v[180:183], v[82:85]
	v_mfma_f32_16x16x32_bf16 v[70:73], v[198:201], v[190:193], v[70:73]
	v_mfma_f32_16x16x32_bf16 v[66:69], v[206:209], v[190:193], v[66:69]
	s_mov_b32 m0, s60
	v_lshl_add_u64 v[210:211], v[214:215], 0, s[40:41]
	s_barrier
	ds_read_b128 v[158:161], v171 offset:49152
	ds_read_b128 v[162:165], v171 offset:50176
	ds_read_b128 v[166:169], v171 offset:51200
	ds_read_b128 v[172:175], v171 offset:52224
	ds_read_b128 v[176:179], v171 offset:53248
	ds_read_b128 v[180:183], v171 offset:54272
	ds_read_b128 v[184:187], v171 offset:55296
	ds_read_b128 v[190:193], v171 offset:56320
	global_load_lds_dwordx4 v[210:211], off
	s_mov_b32 m0, s61
	v_lshl_add_u64 v[210:211], v[216:217], 0, s[40:41]
	global_load_lds_dwordx4 v[210:211], off
	s_waitcnt vmcnt(10)
	s_barrier
	s_waitcnt lgkmcnt(0)
	v_mfma_f32_16x16x32_bf16 v[62:65], v[130:133], v[158:161], v[62:65]
	v_mfma_f32_16x16x32_bf16 v[58:61], v[138:141], v[158:161], v[58:61]
	v_mfma_f32_16x16x32_bf16 v[46:49], v[130:133], v[166:169], v[46:49]
	v_mfma_f32_16x16x32_bf16 v[42:45], v[138:141], v[166:169], v[42:45]
	v_mfma_f32_16x16x32_bf16 v[30:33], v[130:133], v[176:179], v[30:33]
	v_mfma_f32_16x16x32_bf16 v[26:29], v[138:141], v[176:179], v[26:29]
	v_mfma_f32_16x16x32_bf16 v[14:17], v[130:133], v[184:187], v[14:17]
	v_mfma_f32_16x16x32_bf16 v[10:13], v[138:141], v[184:187], v[10:13]
	v_mfma_f32_16x16x32_bf16 v[62:65], v[134:137], v[162:165], v[62:65]
	v_mfma_f32_16x16x32_bf16 v[58:61], v[142:145], v[162:165], v[58:61]
	v_mfma_f32_16x16x32_bf16 v[46:49], v[134:137], v[172:175], v[46:49]
	v_mfma_f32_16x16x32_bf16 v[42:45], v[142:145], v[172:175], v[42:45]
	v_mfma_f32_16x16x32_bf16 v[30:33], v[134:137], v[180:183], v[30:33]
	v_mfma_f32_16x16x32_bf16 v[26:29], v[142:145], v[180:183], v[26:29]
	v_mfma_f32_16x16x32_bf16 v[14:17], v[134:137], v[190:193], v[14:17]
	v_mfma_f32_16x16x32_bf16 v[10:13], v[142:145], v[190:193], v[10:13]
	s_barrier
	s_add_u32 s90, s90, 0x40080
	s_addc_u32 s91, s91, 0
	s_add_i32 s87, s92, s38
	s_mov_b32 m0, s87
	s_nop 0
	global_load_lds_dwordx4 v148, s[90:91]
	s_add_i32 m0, s87, 0x2000
	s_nop 0
	global_load_lds_dwordx4 v152, s[90:91]
	s_add_i32 s94, 0, 0x10000
	v_add_u32_e32 v0, s94, v170
	ds_read_b128 v[130:133], v0
	ds_read_b128 v[134:137], v0 offset:1024
	ds_read_b128 v[138:141], v0 offset:2048
	ds_read_b128 v[142:145], v0 offset:3072
	s_waitcnt vmcnt(6)
	s_barrier
	v_mfma_f32_16x16x32_bf16 v[54:57], v[194:197], v[158:161], v[54:57]
	v_mfma_f32_16x16x32_bf16 v[50:53], v[202:205], v[158:161], v[50:53]
	v_mfma_f32_16x16x32_bf16 v[38:41], v[194:197], v[166:169], v[38:41]
	v_mfma_f32_16x16x32_bf16 v[34:37], v[202:205], v[166:169], v[34:37]
	v_mfma_f32_16x16x32_bf16 v[22:25], v[194:197], v[176:179], v[22:25]
	v_mfma_f32_16x16x32_bf16 v[18:21], v[202:205], v[176:179], v[18:21]
	v_mfma_f32_16x16x32_bf16 v[6:9], v[194:197], v[184:187], v[6:9]
	v_mfma_f32_16x16x32_bf16 v[2:5], v[202:205], v[184:187], v[2:5]
	v_mfma_f32_16x16x32_bf16 v[54:57], v[198:201], v[162:165], v[54:57]
	v_mfma_f32_16x16x32_bf16 v[50:53], v[206:209], v[162:165], v[50:53]
	v_mfma_f32_16x16x32_bf16 v[38:41], v[198:201], v[172:175], v[38:41]
	v_mfma_f32_16x16x32_bf16 v[34:37], v[206:209], v[172:175], v[34:37]
	v_mfma_f32_16x16x32_bf16 v[22:25], v[198:201], v[180:183], v[22:25]
	v_mfma_f32_16x16x32_bf16 v[18:21], v[206:209], v[180:183], v[18:21]
	v_mfma_f32_16x16x32_bf16 v[6:9], v[198:201], v[190:193], v[6:9]
	v_mfma_f32_16x16x32_bf16 v[2:5], v[206:209], v[190:193], v[2:5]
	s_add_i32 s85, s85, 2
	s_add_u32 s88, s88, 0x100
	s_addc_u32 s89, s89, 0
	s_add_u32 s34, s34, 0x100
	s_addc_u32 s79, s79, 0
	s_add_u32 s87, s88, 0xfffc0080
	s_addc_u32 s90, s89, -1
	s_cmp_eq_u32 s85, 12
	s_cselect_b32 s93, s13, s90
	s_cselect_b32 s92, s22, s87
	s_cselect_b32 s91, s7, s79
	s_cselect_b32 s90, s23, s34
	s_cmp_gt_u32 s85, 13
	s_barrier
	s_cbranch_scc0 .LBB0_1209
	s_waitcnt lgkmcnt(0)
	v_mov_b32_e32 v131, v252
	s_lshl_b32 s7, s86, 8
	v_and_b32_e32 v130, 63, v131
	v_or_b32_e32 v0, s72, v130
	v_lshrrev_b32_e32 v0, 1, v0
	v_and_or_b32 v132, v0, 63, s73
	v_add_u32_e32 v134, s7, v132
	v_ashrrev_i32_e32 v135, 31, v134
	v_and_b32_e32 v142, 1, v131
	v_lshlrev_b64 v[134:135], 6, v[134:135]
	v_lshl_add_u64 v[134:135], s[82:83], 0, v[134:135]
	v_lshlrev_b32_e32 v0, 5, v142
	v_lshl_add_u64 v[138:139], v[134:135], 0, v[0:1]
	global_load_dwordx4 v[134:137], v[138:139], off
	s_nop 0
	global_load_dwordx4 v[138:141], v[138:139], off offset:16
	v_lshlrev_b32_e32 v0, 2, v130
	v_cmp_eq_u32_e32 vcc, 0, v142
	s_waitcnt vmcnt(0)
	v_add_f32_e32 v133, v134, v135
	v_add_f32_e32 v134, v136, v137
	v_add_f32_e32 v135, v138, v139
	v_add_f32_e32 v136, v140, v141
	v_add_f32_e32 v133, v133, v134
	v_add_f32_e32 v134, v135, v136
	v_add_f32_e32 v133, v133, v134
	v_xor_b32_e32 v134, 4, v0
	ds_bpermute_b32 v134, v134, v133
	s_and_saveexec_b64 s[22:23], vcc
	s_cbranch_execz .LBB0_1212
	s_waitcnt lgkmcnt(0)
	v_add_f32_e32 v133, v133, v134
	v_fmamk_f32 v133, v133, 0x3a800000, v224
	s_mov_b32 s13, 0x800000
	v_mul_f32_e32 v134, 0x4b800000, v133
	v_cmp_gt_f32_e32 vcc, s13, v133
	v_lshl_add_u32 v132, v132, 2, 0
	v_add_u32_e32 v132, 0x20000, v132
	v_cndmask_b32_e32 v133, v133, v134, vcc
	v_rsq_f32_e32 v133, v133
	s_nop 0
	v_mul_f32_e32 v134, 0x45800000, v133
	v_cndmask_b32_e32 v133, v133, v134, vcc
	ds_write_b32 v132, v133
